# select_rows: wave-wide suffix-sum scan and min all-reduce done with DPP row_shr/row_bcast instead of 6-step ds_bpermute chains
# speedup vs baseline: 1.0098x; 1.0046x over previous
; #define LAS __attribute__((address_space(3)))
; #define GAS __attribute__((address_space(1)))
; __device__ __forceinline__ unsigned skey_of(float f) { const unsigned u = __float_as_uint(f); return u ^ ((unsigned)((int)u >> 31) | 0x80000000u); }
; template <int NJ>
; __device__ __forceinline__ void select_rows(const GAS float* sr0, GAS unsigned long long* mb0, LAS unsigned* hist, LAS unsigned* kbuf, int ntl, int lane) {
;     ...
;     for (int rr = 0; rr < 8; ++rr) {
;         const GAS float* srow = sr0 + (size_t)rr * SEQ;
;         float fv[NJ];
; #pragma unroll
;         for (int j = 0; j < NJ; ++j) fv[j] = srow[64 * j];
;         { unsigned z = 0u; asm volatile("" : "+v"(z));
;           *(LAS u32x4*)(hist + 4 * lane) = (u32x4){z, z, z, z}; if (lane < 2) hist[256 + lane] = z; }
;         __builtin_amdgcn_wave_barrier();
;         unsigned key[NJ];
; #pragma unroll
;         for (int j = 0; j < NJ; ++j) {
;             const float f = fv[j]; const bool ok = (vm >> j) & 1u;
;             key[j] = ok ? skey_of(f) : 0u;
;             const int bk = min(max((int)floorf(f + f) + 128, 0), 255);
;             __hip_atomic_fetch_add(hist + (ok ? bk : 256), 1u, __ATOMIC_RELAXED, __HIP_MEMORY_SCOPE_WORKGROUP);
;         }
.LBB0_382:
	s_lshl_b32 s88, s12, 11
	v_lshl_add_u64 v[2:3], s[88:89], 2, v[8:9]
	s_movk_i32 s0, 0x1000
	s_add_i32 s98, s88, 0x800
	s_mov_b32 s99, s89
	s_waitcnt vmcnt(1)
	v_mov_b32_e32 v45, v51
	v_mov_b32_e32 v10, v52
	v_mov_b32_e32 v11, v53
	v_mov_b32_e32 v12, v54
	v_mov_b32_e32 v13, v55
	v_mov_b32_e32 v14, v56
	v_mov_b32_e32 v15, v57
	v_mov_b32_e32 v16, v58
	v_mov_b32_e32 v17, v59
	v_mov_b32_e32 v18, v60
	v_mov_b32_e32 v19, v61
	v_mov_b32_e32 v20, v62
	v_mov_b32_e32 v21, v63
	v_mov_b32_e32 v22, v64
	v_mov_b32_e32 v23, v65
	v_mov_b32_e32 v24, v66
	v_mov_b32_e32 v25, v67
	v_mov_b32_e32 v26, v68
	v_mov_b32_e32 v27, v69
	v_mov_b32_e32 v28, v70
	v_mov_b32_e32 v29, v71
	v_mov_b32_e32 v30, v72
	v_mov_b32_e32 v31, v73
	v_mov_b32_e32 v32, v74
	v_mov_b32_e32 v33, v75
	v_mov_b32_e32 v34, v76
	v_mov_b32_e32 v35, v77
	v_mov_b32_e32 v36, v78
	v_mov_b32_e32 v37, v79
	v_mov_b32_e32 v42, v80
	v_mov_b32_e32 v43, v81
	v_mov_b32_e32 v44, v82
	v_lshl_add_u64 v[84:85], s[98:99], 2, v[8:9]
	v_add_co_u32_e32 v86, vcc, 0x1000, v84
	s_nop 1
	v_addc_co_u32_e32 v87, vcc, 0, v85, vcc
	global_load_dword v51, v[84:85], off
	global_load_dword v52, v[84:85], off offset:256
	global_load_dword v53, v[84:85], off offset:512
	global_load_dword v54, v[84:85], off offset:768
	global_load_dword v55, v[84:85], off offset:1024
	global_load_dword v56, v[84:85], off offset:1280
	global_load_dword v57, v[84:85], off offset:1536
	global_load_dword v58, v[84:85], off offset:1792
	global_load_dword v59, v[84:85], off offset:2048
	global_load_dword v60, v[84:85], off offset:2304
	global_load_dword v61, v[84:85], off offset:2560
	global_load_dword v62, v[84:85], off offset:2816
	global_load_dword v63, v[84:85], off offset:3072
	global_load_dword v64, v[84:85], off offset:3328
	global_load_dword v65, v[84:85], off offset:3584
	global_load_dword v66, v[84:85], off offset:3840
	global_load_dword v67, v[86:87], off
	global_load_dword v68, v[86:87], off offset:256
	global_load_dword v69, v[86:87], off offset:512
	global_load_dword v70, v[86:87], off offset:768
	global_load_dword v71, v[86:87], off offset:1024
	global_load_dword v72, v[86:87], off offset:1280
	global_load_dword v73, v[86:87], off offset:1536
	global_load_dword v74, v[86:87], off offset:1792
	global_load_dword v75, v[86:87], off offset:2048
	global_load_dword v76, v[86:87], off offset:2304
	global_load_dword v77, v[86:87], off offset:2560
	global_load_dword v78, v[86:87], off offset:2816
	global_load_dword v79, v[86:87], off offset:3072
	global_load_dword v80, v[86:87], off offset:3328
	global_load_dword v81, v[86:87], off offset:3584
	global_load_dword v82, v[86:87], off offset:3840
	v_mov_b32_e32 v2, 0
	s_nop 0
	v_mov_b32_e32 v3, v2
	v_mov_b32_e32 v4, v2
	v_mov_b32_e32 v5, v2
	ds_write_b128 v7, v[2:5]
	s_and_saveexec_b64 s[0:1], s[74:75]
	v_add_u32_e32 v3, v7, v38
	ds_write_b32 v3, v2 offset:1024
	s_or_b64 exec, exec, s[0:1]
	v_add_f32_e32 v2, v45, v45
	v_floor_f32_e32 v2, v2
	v_cvt_i32_f32_e32 v2, v2
	v_add_f32_e32 v3, v10, v10
	v_floor_f32_e32 v3, v3
	v_cvt_i32_f32_e32 v3, v3
	v_max_i32_e32 v2, 0xffffff80, v2
	v_add_u32_e32 v2, 0x80, v2
	v_min_u32_e32 v2, 0xff, v2
	v_cndmask_b32_e64 v2, v2, v226, s[94:95]
	v_lshl_add_u32 v2, v2, 2, s6
	ds_add_u32 v2, v223
	v_max_i32_e32 v2, 0xffffff80, v3
	v_add_f32_e32 v3, v11, v11
	v_floor_f32_e32 v3, v3
	v_add_u32_e32 v2, 0x80, v2
	v_cvt_i32_f32_e32 v3, v3
	v_min_u32_e32 v2, 0xff, v2
	v_cndmask_b32_e64 v2, v2, v226, s[14:15]
	v_lshl_add_u32 v2, v2, 2, s6
	ds_add_u32 v2, v223
	v_max_i32_e32 v2, 0xffffff80, v3
	v_add_f32_e32 v3, v12, v12
	v_floor_f32_e32 v3, v3
	v_add_u32_e32 v2, 0x80, v2
	v_cvt_i32_f32_e32 v3, v3
	v_min_u32_e32 v2, 0xff, v2
	v_cndmask_b32_e64 v2, v2, v226, s[16:17]
	v_lshl_add_u32 v2, v2, 2, s6
	ds_add_u32 v2, v223
	v_max_i32_e32 v2, 0xffffff80, v3
	v_add_f32_e32 v3, v13, v13
	v_floor_f32_e32 v3, v3
	v_add_u32_e32 v2, 0x80, v2
	v_cvt_i32_f32_e32 v3, v3
	v_min_u32_e32 v2, 0xff, v2
	v_cndmask_b32_e64 v2, v2, v226, s[18:19]
	v_lshl_add_u32 v2, v2, 2, s6
	ds_add_u32 v2, v223
	v_max_i32_e32 v2, 0xffffff80, v3
	v_add_f32_e32 v3, v14, v14
	v_floor_f32_e32 v3, v3
	v_add_u32_e32 v2, 0x80, v2
	v_cvt_i32_f32_e32 v3, v3
	v_min_u32_e32 v2, 0xff, v2
	v_cndmask_b32_e64 v2, v2, v226, s[24:25]
	v_lshl_add_u32 v2, v2, 2, s6
	ds_add_u32 v2, v223
	v_max_i32_e32 v2, 0xffffff80, v3
	v_add_f32_e32 v3, v15, v15
	v_floor_f32_e32 v3, v3
	v_add_u32_e32 v2, 0x80, v2
	v_cvt_i32_f32_e32 v3, v3
	v_min_u32_e32 v2, 0xff, v2
	v_cndmask_b32_e64 v2, v2, v226, s[26:27]
	v_lshl_add_u32 v2, v2, 2, s6
	ds_add_u32 v2, v223
	v_max_i32_e32 v2, 0xffffff80, v3
	v_add_f32_e32 v3, v16, v16
	v_floor_f32_e32 v3, v3
	v_add_u32_e32 v2, 0x80, v2
	v_cvt_i32_f32_e32 v3, v3
	v_min_u32_e32 v2, 0xff, v2
	v_cndmask_b32_e64 v2, v2, v226, s[28:29]
	v_lshl_add_u32 v2, v2, 2, s6
	ds_add_u32 v2, v223
	v_max_i32_e32 v2, 0xffffff80, v3
	v_add_f32_e32 v3, v17, v17
	v_floor_f32_e32 v3, v3
	v_add_u32_e32 v2, 0x80, v2
	v_cvt_i32_f32_e32 v3, v3
	v_min_u32_e32 v2, 0xff, v2
	v_cndmask_b32_e64 v2, v2, v226, s[30:31]
	v_lshl_add_u32 v2, v2, 2, s6
	ds_add_u32 v2, v223
	v_max_i32_e32 v2, 0xffffff80, v3
	v_add_f32_e32 v3, v18, v18
	v_floor_f32_e32 v3, v3
	v_add_u32_e32 v2, 0x80, v2
	v_cvt_i32_f32_e32 v3, v3
	v_min_u32_e32 v2, 0xff, v2
	v_cndmask_b32_e64 v2, v2, v226, s[34:35]
	v_lshl_add_u32 v2, v2, 2, s6
	ds_add_u32 v2, v223
	v_max_i32_e32 v2, 0xffffff80, v3
	v_add_f32_e32 v3, v19, v19
	v_floor_f32_e32 v3, v3
	v_add_u32_e32 v2, 0x80, v2
	v_cvt_i32_f32_e32 v3, v3
	v_min_u32_e32 v2, 0xff, v2
	v_cndmask_b32_e64 v2, v2, v226, s[36:37]
	v_lshl_add_u32 v2, v2, 2, s6
	ds_add_u32 v2, v223
	v_max_i32_e32 v2, 0xffffff80, v3
	v_add_f32_e32 v3, v20, v20
; #define LAS __attribute__((address_space(3)))
; template <int NJ>
; __device__ __forceinline__ void select_rows(const GAS float* sr0, GAS unsigned long long* mb0, LAS unsigned* hist, LAS unsigned* kbuf, int ntl, int lane) {
;     ...
;             __hip_atomic_fetch_add(hist + (ok ? bk : 256), 1u, __ATOMIC_RELAXED, __HIP_MEMORY_SCOPE_WORKGROUP);
;         }
;         __builtin_amdgcn_wave_barrier();
;         asm volatile("s_waitcnt lgkmcnt(0)" ::: "memory");
;         unsigned B, rem, C;
;         {
;             const u32x4 hv = *(const LAS u32x4*)(hist + 4 * lane);
;             const unsigned s4 = hv.x + hv.y + hv.z + hv.w;
;             unsigned S = s4;
; #pragma unroll
;             for (int off = 1; off < 64; off <<= 1) { const unsigned n = __shfl_down(S, off); if (lane + off < 64) S += n; }
;             const unsigned excl = S - s4;
;             const bool mine = (excl < 256u) && (256u <= S);
;             unsigned dl, above, cnt, c = excl;
;             if (c + hv.w >= 256u) { dl = 3; above = c; cnt = hv.w; } else { c += hv.w; if (c + hv.z >= 256u) { dl = 2; above = c; cnt = hv.z; } else { c += hv.z; if (c + hv.y >= 256u) { dl = 1; above = c; cnt = hv.y; } else { c += hv.y; dl = 0; above = c; cnt = hv.x; } } }
;             const unsigned long long bm = __ballot(mine);
;             const int src = bm ? (int)__builtin_ctzll(bm) : 0;
;             B = (unsigned)__builtin_amdgcn_readlane((int)(4 * lane + dl), src);
;             rem = 256u - (unsigned)__builtin_amdgcn_readlane((int)above, src);
;             C = (unsigned)__builtin_amdgcn_readlane((int)cnt, src);
	v_floor_f32_e32 v3, v3
	v_add_u32_e32 v2, 0x80, v2
	v_cvt_i32_f32_e32 v3, v3
	v_min_u32_e32 v2, 0xff, v2
	v_cndmask_b32_e64 v2, v2, v226, s[38:39]
	v_lshl_add_u32 v2, v2, 2, s6
	ds_add_u32 v2, v223
	v_max_i32_e32 v2, 0xffffff80, v3
	v_add_f32_e32 v3, v21, v21
	v_floor_f32_e32 v3, v3
	v_add_u32_e32 v2, 0x80, v2
	v_cvt_i32_f32_e32 v3, v3
	v_min_u32_e32 v2, 0xff, v2
	v_cndmask_b32_e64 v2, v2, v226, s[40:41]
	v_lshl_add_u32 v2, v2, 2, s6
	ds_add_u32 v2, v223
	v_max_i32_e32 v2, 0xffffff80, v3
	v_add_f32_e32 v3, v22, v22
	v_floor_f32_e32 v3, v3
	v_add_u32_e32 v2, 0x80, v2
	v_cvt_i32_f32_e32 v3, v3
	v_min_u32_e32 v2, 0xff, v2
	v_cndmask_b32_e64 v2, v2, v226, s[42:43]
	v_lshl_add_u32 v2, v2, 2, s6
	ds_add_u32 v2, v223
	v_max_i32_e32 v2, 0xffffff80, v3
	v_add_f32_e32 v3, v23, v23
	v_floor_f32_e32 v3, v3
	v_add_u32_e32 v2, 0x80, v2
	v_cvt_i32_f32_e32 v3, v3
	v_min_u32_e32 v2, 0xff, v2
	v_cndmask_b32_e64 v2, v2, v226, s[44:45]
	v_lshl_add_u32 v2, v2, 2, s6
	ds_add_u32 v2, v223
	v_max_i32_e32 v2, 0xffffff80, v3
	v_add_f32_e32 v3, v24, v24
	v_floor_f32_e32 v3, v3
	v_add_u32_e32 v2, 0x80, v2
	v_cvt_i32_f32_e32 v3, v3
	v_min_u32_e32 v2, 0xff, v2
	v_cndmask_b32_e64 v2, v2, v226, s[46:47]
	v_lshl_add_u32 v2, v2, 2, s6
	ds_add_u32 v2, v223
	v_max_i32_e32 v2, 0xffffff80, v3
	v_add_f32_e32 v3, v25, v25
	v_floor_f32_e32 v3, v3
	v_add_u32_e32 v2, 0x80, v2
	v_cvt_i32_f32_e32 v3, v3
	v_min_u32_e32 v2, 0xff, v2
	v_cndmask_b32_e64 v2, v2, v226, s[48:49]
	v_lshl_add_u32 v2, v2, 2, s6
	ds_add_u32 v2, v223
	v_max_i32_e32 v2, 0xffffff80, v3
	v_add_f32_e32 v3, v26, v26
	v_floor_f32_e32 v3, v3
	v_add_u32_e32 v2, 0x80, v2
	v_cvt_i32_f32_e32 v3, v3
	v_min_u32_e32 v2, 0xff, v2
	v_cndmask_b32_e64 v2, v2, v226, s[50:51]
	v_lshl_add_u32 v2, v2, 2, s6
	ds_add_u32 v2, v223
	v_max_i32_e32 v2, 0xffffff80, v3
	v_add_f32_e32 v3, v27, v27
	v_floor_f32_e32 v3, v3
	v_add_u32_e32 v2, 0x80, v2
	v_cvt_i32_f32_e32 v3, v3
	v_min_u32_e32 v2, 0xff, v2
	v_cndmask_b32_e64 v2, v2, v226, s[52:53]
	v_lshl_add_u32 v2, v2, 2, s6
	ds_add_u32 v2, v223
	v_max_i32_e32 v2, 0xffffff80, v3
	v_add_f32_e32 v3, v28, v28
	v_floor_f32_e32 v3, v3
	v_add_u32_e32 v2, 0x80, v2
	v_cvt_i32_f32_e32 v3, v3
	v_min_u32_e32 v2, 0xff, v2
	v_cndmask_b32_e64 v2, v2, v226, s[54:55]
	v_lshl_add_u32 v2, v2, 2, s6
	ds_add_u32 v2, v223
	v_max_i32_e32 v2, 0xffffff80, v3
	v_add_f32_e32 v3, v29, v29
	v_floor_f32_e32 v3, v3
	v_add_u32_e32 v2, 0x80, v2
	v_cvt_i32_f32_e32 v3, v3
	v_min_u32_e32 v2, 0xff, v2
	v_cndmask_b32_e64 v2, v2, v226, s[64:65]
	v_lshl_add_u32 v2, v2, 2, s6
	ds_add_u32 v2, v223
	v_max_i32_e32 v2, 0xffffff80, v3
	v_add_f32_e32 v3, v30, v30
	v_floor_f32_e32 v3, v3
	v_add_u32_e32 v2, 0x80, v2
	v_cvt_i32_f32_e32 v3, v3
	v_min_u32_e32 v2, 0xff, v2
	v_cndmask_b32_e64 v2, v2, v226, s[66:67]
	v_lshl_add_u32 v2, v2, 2, s6
	ds_add_u32 v2, v223
	v_max_i32_e32 v2, 0xffffff80, v3
	v_add_f32_e32 v3, v31, v31
	v_floor_f32_e32 v3, v3
	v_add_u32_e32 v2, 0x80, v2
	v_cvt_i32_f32_e32 v3, v3
	v_min_u32_e32 v2, 0xff, v2
	v_cndmask_b32_e64 v2, v2, v226, s[70:71]
	v_lshl_add_u32 v2, v2, 2, s6
	ds_add_u32 v2, v223
	v_max_i32_e32 v2, 0xffffff80, v3
	v_add_f32_e32 v3, v32, v32
	v_floor_f32_e32 v3, v3
	v_add_u32_e32 v2, 0x80, v2
	v_cvt_i32_f32_e32 v3, v3
	v_min_u32_e32 v2, 0xff, v2
	v_cndmask_b32_e64 v2, v2, v226, s[72:73]
	v_lshl_add_u32 v2, v2, 2, s6
	ds_add_u32 v2, v223
	v_max_i32_e32 v2, 0xffffff80, v3
	v_add_f32_e32 v3, v33, v33
	v_floor_f32_e32 v3, v3
	v_add_u32_e32 v2, 0x80, v2
	v_cvt_i32_f32_e32 v3, v3
	v_min_u32_e32 v2, 0xff, v2
	v_cndmask_b32_e64 v2, v2, v226, s[76:77]
	v_lshl_add_u32 v2, v2, 2, s6
	ds_add_u32 v2, v223
	v_max_i32_e32 v2, 0xffffff80, v3
	v_add_f32_e32 v3, v34, v34
	v_floor_f32_e32 v3, v3
	v_add_u32_e32 v2, 0x80, v2
	v_cvt_i32_f32_e32 v3, v3
	v_min_u32_e32 v2, 0xff, v2
	v_cndmask_b32_e64 v2, v2, v226, s[78:79]
	v_lshl_add_u32 v2, v2, 2, s6
	ds_add_u32 v2, v223
	v_max_i32_e32 v2, 0xffffff80, v3
	v_add_f32_e32 v3, v35, v35
	v_floor_f32_e32 v3, v3
	v_add_u32_e32 v2, 0x80, v2
	v_cvt_i32_f32_e32 v3, v3
	v_min_u32_e32 v2, 0xff, v2
	v_cndmask_b32_e64 v2, v2, v226, s[84:85]
	v_lshl_add_u32 v2, v2, 2, s6
	ds_add_u32 v2, v223
	v_max_i32_e32 v2, 0xffffff80, v3
	v_add_f32_e32 v3, v36, v36
	v_floor_f32_e32 v3, v3
	v_add_u32_e32 v2, 0x80, v2
	v_cvt_i32_f32_e32 v3, v3
	v_min_u32_e32 v2, 0xff, v2
	v_cndmask_b32_e64 v2, v2, v226, s[90:91]
	v_lshl_add_u32 v2, v2, 2, s6
	ds_add_u32 v2, v223
	v_max_i32_e32 v2, 0xffffff80, v3
	v_add_f32_e32 v3, v37, v37
	v_floor_f32_e32 v3, v3
	v_add_u32_e32 v2, 0x80, v2
	v_cvt_i32_f32_e32 v3, v3
	v_min_u32_e32 v2, 0xff, v2
	v_cndmask_b32_e64 v2, v2, v226, s[92:93]
	v_lshl_add_u32 v2, v2, 2, s6
	ds_add_u32 v2, v223
	v_max_i32_e32 v2, 0xffffff80, v3
	v_add_f32_e32 v3, v42, v42
	v_floor_f32_e32 v3, v3
	v_add_u32_e32 v2, 0x80, v2
	v_cvt_i32_f32_e32 v3, v3
	v_min_u32_e32 v2, 0xff, v2
	v_cndmask_b32_e64 v2, v2, v226, s[8:9]
	v_lshl_add_u32 v2, v2, 2, s6
	ds_add_u32 v2, v223
	v_max_i32_e32 v2, 0xffffff80, v3
	v_add_f32_e32 v3, v43, v43
	v_floor_f32_e32 v3, v3
	v_add_u32_e32 v2, 0x80, v2
	v_cvt_i32_f32_e32 v3, v3
	v_readlane_b32 s0, v254, 33
	v_min_u32_e32 v2, 0xff, v2
	v_readlane_b32 s1, v254, 34
	s_nop 1
	v_cndmask_b32_e64 v2, v2, v226, s[0:1]
	v_lshl_add_u32 v2, v2, 2, s6
	ds_add_u32 v2, v223
	v_max_i32_e32 v2, 0xffffff80, v3
	v_add_f32_e32 v3, v44, v44
	v_floor_f32_e32 v3, v3
	v_add_u32_e32 v2, 0x80, v2
	v_cvt_i32_f32_e32 v3, v3
	v_readlane_b32 s0, v254, 35
	v_min_u32_e32 v2, 0xff, v2
	v_readlane_b32 s1, v254, 36
	s_nop 1
	v_cndmask_b32_e64 v2, v2, v226, s[0:1]
	v_lshl_add_u32 v2, v2, 2, s6
	ds_add_u32 v2, v223
	v_max_i32_e32 v2, 0xffffff80, v3
	v_add_u32_e32 v2, 0x80, v2
	v_readlane_b32 s0, v254, 37
	v_min_u32_e32 v2, 0xff, v2
	v_readlane_b32 s1, v254, 38
	s_nop 1
	v_cndmask_b32_e64 v2, v2, v226, s[0:1]
	v_lshl_add_u32 v2, v2, 2, s6
	ds_add_u32 v2, v223
	s_waitcnt lgkmcnt(0)
	ds_read_b128 v[2:5], v7
	v_readlane_b32 s0, v254, 41
	v_readlane_b32 s1, v254, 42
	s_waitcnt lgkmcnt(0)
	v_add_u32_e32 v46, v2, v3
	v_add3_u32 v47, v46, v4, v5
	v_mov_b32_e32 v46, v47
	s_nop 1
	v_add_u32_dpp v46, v46, v46 row_shr:1 row_mask:0xf bank_mask:0xf bound_ctrl:0
	s_nop 1
	v_add_u32_dpp v46, v46, v46 row_shr:2 row_mask:0xf bank_mask:0xf bound_ctrl:0
	s_nop 1
	v_add_u32_dpp v46, v46, v46 row_shr:4 row_mask:0xf bank_mask:0xf bound_ctrl:0
	s_nop 1
	v_add_u32_dpp v46, v46, v46 row_shr:8 row_mask:0xf bank_mask:0xf bound_ctrl:0
	s_nop 1
	v_add_u32_dpp v46, v46, v46 row_bcast:15 row_mask:0xa bank_mask:0xf
	s_nop 1
	v_add_u32_dpp v46, v46, v46 row_bcast:31 row_mask:0xc bank_mask:0xf
	s_nop 1
	v_readlane_b32 s0, v46, 63
	s_nop 1
	v_sub_u32_e32 v48, s0, v46
	v_add_u32_e32 v46, v48, v47
	v_mov_b32_e32 v47, v48
	v_add_u32_e32 v50, v47, v5
	v_cmp_gt_u32_e32 vcc, s63, v50
	v_mov_b32_e32 v48, 3
	v_mov_b32_e32 v49, v47
	s_and_saveexec_b64 s[0:1], vcc
	s_cbranch_execz .LBB0_388
; template <int NJ>
; __device__ __forceinline__ void select_rows(const GAS float* sr0, GAS unsigned long long* mb0, LAS unsigned* hist, LAS unsigned* kbuf, int ntl, int lane) {
;     ...
;             if (c + hv.w >= 256u) { dl = 3; above = c; cnt = hv.w; } else { c += hv.w; if (c + hv.z >= 256u) { dl = 2; above = c; cnt = hv.z; } else { c += hv.z; if (c + hv.y >= 256u) { dl = 1; above = c; cnt = hv.y; } else { c += hv.y; dl = 0; above = c; cnt = hv.x; } } }
	v_add_u32_e32 v5, v50, v4
	v_cmp_gt_u32_e32 vcc, s63, v5
	v_mov_b32_e32 v48, 2
	s_and_saveexec_b64 s[2:3], vcc
	v_add_u32_e32 v4, v5, v3
	s_movk_i32 s4, 0xff
	v_cmp_lt_u32_e32 vcc, s4, v4
	s_nop 1
	v_cndmask_b32_e64 v48, 0, 1, vcc
	v_cndmask_b32_e32 v50, v4, v5, vcc
	v_cndmask_b32_e32 v4, v2, v3, vcc
	s_or_b64 exec, exec, s[2:3]
	v_mov_b32_e32 v5, v4
	v_mov_b32_e32 v49, v50

; #define WL1(J) if constexpr (J < NJ) { const unsigned long long w_ = __ballot(key[J] >= tau); const unsigned wl_ = (unsigned)w_, wh_ = (unsigned)(w_ >> 32); \
;                 asm volatile("s_nop 3\n\tv_writelane_b32 %0, %2, " #J "\n\tv_writelane_b32 %1, %3, " #J : "+v"(mlo), "+v"(mhi) : "s"(wl_), "s"(wh_)); }
; template <int NJ>
; __device__ __forceinline__ void select_rows(const GAS float* sr0, GAS unsigned long long* mb0, LAS unsigned* hist, LAS unsigned* kbuf, int ntl, int lane) {
;     ...
;             unsigned t = (have && cgt < rem) ? mykey : 0xffffffffu;
; #pragma unroll
;             for (int o = 1; o < 64; o <<= 1) t = min(t, (unsigned)__shfl_xor((int)t, o));
;             tau = t;
;             const unsigned long long eqm = __ballot(have && mykey == tau);
;             cnteq = (unsigned)__popcll(eqm);
;             remf = rem - (unsigned)__builtin_amdgcn_readlane((int)cgt, eqm ? (int)__builtin_ctzll(eqm) : 0);
;             generic = cnteq > remf;
;         }
;         unsigned mlo = 0u, mhi = 0u;
;         if (!generic) {
;     ...
;             WL1(0) WL1(1) WL1(2) WL1(3) WL1(4) WL1(5) WL1(6) WL1(7) WL1(8) WL1(9) WL1(10) WL1(11) WL1(12) WL1(13) WL1(14) WL1(15)
;             WL1(16) WL1(17) WL1(18) WL1(19) WL1(20) WL1(21) WL1(22) WL1(23) WL1(24) WL1(25) WL1(26) WL1(27) WL1(28) WL1(29) WL1(30) WL1(31)
.LBB0_521:
	s_sub_i32 s2, 0x100, s8
	v_cmp_gt_u32_e64 s[0:1], s2, v3
	v_and_b32_e32 v45, 64, v224
	s_and_b64 s[0:1], vcc, s[0:1]
	v_add_u32_e32 v45, 64, v45
	v_xor_b32_e32 v46, 1, v224
	s_waitcnt lgkmcnt(0)
	v_cndmask_b32_e64 v5, -1, v2, s[0:1]
	s_nop 1
	v_min_u32_dpp v5, v5, v5 row_shr:1 row_mask:0xf bank_mask:0xf
	s_nop 1
	v_min_u32_dpp v5, v5, v5 row_shr:2 row_mask:0xf bank_mask:0xf
	s_nop 1
	v_min_u32_dpp v5, v5, v5 row_shr:4 row_mask:0xf bank_mask:0xf
	s_nop 1
	v_min_u32_dpp v5, v5, v5 row_shr:8 row_mask:0xf bank_mask:0xf
	s_nop 1
	v_min_u32_dpp v5, v5, v5 row_bcast:15 row_mask:0xa bank_mask:0xf
	s_nop 1
	v_min_u32_dpp v5, v5, v5 row_bcast:31 row_mask:0xc bank_mask:0xf
	s_nop 1
	v_readlane_b32 s0, v5, 63
	s_nop 1
	v_mov_b32_e32 v5, s0
	v_cmp_eq_u32_e64 s[0:1], v2, v5
	s_and_b64 s[0:1], vcc, s[0:1]
	s_nop 0
	v_cndmask_b32_e64 v2, 0, 1, s[0:1]
	v_cmp_ne_u32_e32 vcc, 0, v2
	s_bcnt1_i32_b64 s0, vcc
	s_ff1_i32_b64 s1, vcc
	s_cmp_lg_u64 vcc, 0
	s_cselect_b32 s1, s1, 0
	v_readlane_b32 s1, v3, s1
	s_sub_i32 s1, s2, s1
	s_cmp_ge_u32 s1, s0
	s_mov_b64 s[0:1], -1
	s_cbranch_scc0 .LBB0_523
	v_cmp_ge_u32_e32 vcc, v4, v5
	v_mov_b32_e32 v2, v0
	v_mov_b32_e32 v3, v0
	s_nop 3
	v_writelane_b32 v2, vcc_lo, 0
	v_writelane_b32 v3, vcc_hi, 0
	v_cmp_ge_u32_e32 vcc, v10, v5
	s_nop 3
	v_writelane_b32 v2, vcc_lo, 1
	v_writelane_b32 v3, vcc_hi, 1
	v_cmp_ge_u32_e32 vcc, v11, v5
	s_nop 3
	v_writelane_b32 v2, vcc_lo, 2
	v_writelane_b32 v3, vcc_hi, 2
	v_cmp_ge_u32_e32 vcc, v12, v5
	s_nop 3
	v_writelane_b32 v2, vcc_lo, 3
	v_writelane_b32 v3, vcc_hi, 3
	v_cmp_ge_u32_e32 vcc, v13, v5
	s_nop 3
	v_writelane_b32 v2, vcc_lo, 4
	v_writelane_b32 v3, vcc_hi, 4
	v_cmp_ge_u32_e32 vcc, v14, v5
	s_nop 3
	v_writelane_b32 v2, vcc_lo, 5
	v_writelane_b32 v3, vcc_hi, 5
	v_cmp_ge_u32_e32 vcc, v15, v5
	s_nop 3
	v_writelane_b32 v2, vcc_lo, 6
	v_writelane_b32 v3, vcc_hi, 6
	v_cmp_ge_u32_e32 vcc, v16, v5
	s_nop 3
	v_writelane_b32 v2, vcc_lo, 7
	v_writelane_b32 v3, vcc_hi, 7
	v_cmp_ge_u32_e32 vcc, v17, v5
	s_nop 3
	v_writelane_b32 v2, vcc_lo, 8
	v_writelane_b32 v3, vcc_hi, 8
	v_cmp_ge_u32_e32 vcc, v18, v5
	s_nop 3
	v_writelane_b32 v2, vcc_lo, 9
	v_writelane_b32 v3, vcc_hi, 9
	v_cmp_ge_u32_e32 vcc, v19, v5
	s_nop 3
	v_writelane_b32 v2, vcc_lo, 10
	v_writelane_b32 v3, vcc_hi, 10
	v_cmp_ge_u32_e32 vcc, v20, v5
	s_nop 3
	v_writelane_b32 v2, vcc_lo, 11
	v_writelane_b32 v3, vcc_hi, 11
	v_cmp_ge_u32_e32 vcc, v21, v5
	s_nop 3
	v_writelane_b32 v2, vcc_lo, 12
	v_writelane_b32 v3, vcc_hi, 12
	v_cmp_ge_u32_e32 vcc, v22, v5
	s_nop 3
	v_writelane_b32 v2, vcc_lo, 13
	v_writelane_b32 v3, vcc_hi, 13
	v_cmp_ge_u32_e32 vcc, v23, v5
	s_nop 3
	v_writelane_b32 v2, vcc_lo, 14
	v_writelane_b32 v3, vcc_hi, 14
	v_cmp_ge_u32_e32 vcc, v24, v5
	s_nop 3
	v_writelane_b32 v2, vcc_lo, 15
	v_writelane_b32 v3, vcc_hi, 15
	v_cmp_ge_u32_e32 vcc, v25, v5
	s_nop 3
	v_writelane_b32 v2, vcc_lo, 16
	v_writelane_b32 v3, vcc_hi, 16
	v_cmp_ge_u32_e32 vcc, v26, v5
	s_nop 3
	v_writelane_b32 v2, vcc_lo, 17
	v_writelane_b32 v3, vcc_hi, 17
	v_cmp_ge_u32_e32 vcc, v27, v5
	s_nop 3
	v_writelane_b32 v2, vcc_lo, 18
	v_writelane_b32 v3, vcc_hi, 18
	v_cmp_ge_u32_e32 vcc, v28, v5
	s_nop 3
	v_writelane_b32 v2, vcc_lo, 19
	v_writelane_b32 v3, vcc_hi, 19
	v_cmp_ge_u32_e32 vcc, v29, v5
	s_nop 3
	v_writelane_b32 v2, vcc_lo, 20
	v_writelane_b32 v3, vcc_hi, 20
	v_cmp_ge_u32_e32 vcc, v30, v5
	s_nop 3
	v_writelane_b32 v2, vcc_lo, 21
	v_writelane_b32 v3, vcc_hi, 21
	v_cmp_ge_u32_e32 vcc, v31, v5
	s_nop 3
	v_writelane_b32 v2, vcc_lo, 22
	v_writelane_b32 v3, vcc_hi, 22
	v_cmp_ge_u32_e32 vcc, v32, v5
	s_nop 3
	v_writelane_b32 v2, vcc_lo, 23
	v_writelane_b32 v3, vcc_hi, 23
	v_cmp_ge_u32_e32 vcc, v33, v5
	s_nop 3
	v_writelane_b32 v2, vcc_lo, 24
	v_writelane_b32 v3, vcc_hi, 24
	v_cmp_ge_u32_e32 vcc, v34, v5
	s_nop 3
	v_writelane_b32 v2, vcc_lo, 25
	v_writelane_b32 v3, vcc_hi, 25
	v_cmp_ge_u32_e32 vcc, v35, v5
	s_nop 3
	v_writelane_b32 v2, vcc_lo, 26
	v_writelane_b32 v3, vcc_hi, 26
	v_cmp_ge_u32_e32 vcc, v36, v5
	s_nop 3
	v_writelane_b32 v2, vcc_lo, 27
	v_writelane_b32 v3, vcc_hi, 27
	v_cmp_ge_u32_e32 vcc, v37, v5
	s_nop 3
	v_writelane_b32 v2, vcc_lo, 28
	v_writelane_b32 v3, vcc_hi, 28
	v_cmp_ge_u32_e32 vcc, v42, v5
	s_nop 3
	v_writelane_b32 v2, vcc_lo, 29
	v_writelane_b32 v3, vcc_hi, 29
	v_cmp_ge_u32_e32 vcc, v43, v5
	s_nop 3
	v_writelane_b32 v2, vcc_lo, 30
	v_writelane_b32 v3, vcc_hi, 30
	v_cmp_ge_u32_e32 vcc, v44, v5
	s_mov_b64 s[0:1], 0
	s_nop 3
	v_writelane_b32 v2, vcc_lo, 31
	v_writelane_b32 v3, vcc_hi, 31

; #define LAS __attribute__((address_space(3)))
; #define GAS __attribute__((address_space(1)))
; __device__ __forceinline__ unsigned skey_of(float f) { const unsigned u = __float_as_uint(f); return u ^ ((unsigned)((int)u >> 31) | 0x80000000u); }
; template <int NJ>
; __device__ __forceinline__ void select_rows(const GAS float* sr0, GAS unsigned long long* mb0, LAS unsigned* hist, LAS unsigned* kbuf, int ntl, int lane) {
;     ...
;     for (int rr = 0; rr < 8; ++rr) {
;         const GAS float* srow = sr0 + (size_t)rr * SEQ;
;         float fv[NJ];
; #pragma unroll
;         for (int j = 0; j < NJ; ++j) fv[j] = srow[64 * j];
;         { unsigned z = 0u; asm volatile("" : "+v"(z));
;           *(LAS u32x4*)(hist + 4 * lane) = (u32x4){z, z, z, z}; if (lane < 2) hist[256 + lane] = z; }
;         __builtin_amdgcn_wave_barrier();
;         unsigned key[NJ];
; #pragma unroll
;         for (int j = 0; j < NJ; ++j) {
;             const float f = fv[j]; const bool ok = (vm >> j) & 1u;
;             key[j] = ok ? skey_of(f) : 0u;
;             const int bk = min(max((int)floorf(f + f) + 128, 0), 255);
;             __hip_atomic_fetch_add(hist + (ok ? bk : 256), 1u, __ATOMIC_RELAXED, __HIP_MEMORY_SCOPE_WORKGROUP);
;         }
.LBB0_533:
	s_lshl_b32 s88, s7, 11
	v_lshl_add_u64 v[2:3], s[88:89], 2, v[8:9]
	global_load_dword v33, v[2:3], off
	global_load_dword v10, v[2:3], off offset:256
	global_load_dword v11, v[2:3], off offset:512
	global_load_dword v12, v[2:3], off offset:768
	global_load_dword v13, v[2:3], off offset:1024
	global_load_dword v14, v[2:3], off offset:1280
	global_load_dword v15, v[2:3], off offset:1536
	global_load_dword v16, v[2:3], off offset:1792
	global_load_dword v17, v[2:3], off offset:2048
	global_load_dword v18, v[2:3], off offset:2304
	global_load_dword v19, v[2:3], off offset:2560
	global_load_dword v20, v[2:3], off offset:2816
	global_load_dword v21, v[2:3], off offset:3072
	global_load_dword v22, v[2:3], off offset:3328
	global_load_dword v23, v[2:3], off offset:3584
	global_load_dword v24, v[2:3], off offset:3840
	s_movk_i32 s0, 0x1000
	v_add_co_u32_e32 v2, vcc, s0, v2
	s_nop 1
	v_addc_co_u32_e32 v3, vcc, 0, v3, vcc
	global_load_dword v25, v[2:3], off
	global_load_dword v26, v[2:3], off offset:256
	global_load_dword v27, v[2:3], off offset:512
	global_load_dword v28, v[2:3], off offset:768
	global_load_dword v29, v[2:3], off offset:1024
	global_load_dword v30, v[2:3], off offset:1280
	global_load_dword v31, v[2:3], off offset:1536
	global_load_dword v32, v[2:3], off offset:1792
	v_mov_b32_e32 v2, 0
	s_nop 0
	v_mov_b32_e32 v3, v2
	v_mov_b32_e32 v4, v2
	v_mov_b32_e32 v5, v2
	ds_write_b128 v7, v[2:5]
	s_and_saveexec_b64 s[0:1], s[74:75]
	v_add_u32_e32 v3, v7, v38
	ds_write_b32 v3, v2 offset:1024
	s_or_b64 exec, exec, s[0:1]
	s_waitcnt vmcnt(23)
	v_add_f32_e32 v2, v33, v33
	v_floor_f32_e32 v2, v2
	v_cvt_i32_f32_e32 v2, v2
	s_waitcnt vmcnt(22)
	v_add_f32_e32 v3, v10, v10
	v_floor_f32_e32 v3, v3
	v_cvt_i32_f32_e32 v3, v3
	v_max_i32_e32 v2, 0xffffff80, v2
	v_add_u32_e32 v2, 0x80, v2
	v_min_u32_e32 v2, 0xff, v2
	v_cndmask_b32_e64 v2, v2, v226, s[14:15]
	v_lshl_add_u32 v2, v2, 2, s6
	ds_add_u32 v2, v223
	v_max_i32_e32 v2, 0xffffff80, v3
	s_waitcnt vmcnt(21)
	v_add_f32_e32 v3, v11, v11
	v_floor_f32_e32 v3, v3
	v_add_u32_e32 v2, 0x80, v2
	v_cvt_i32_f32_e32 v3, v3
	v_min_u32_e32 v2, 0xff, v2
	v_cndmask_b32_e64 v2, v2, v226, s[16:17]
	v_lshl_add_u32 v2, v2, 2, s6
	ds_add_u32 v2, v223
	v_max_i32_e32 v2, 0xffffff80, v3
	s_waitcnt vmcnt(20)
	v_add_f32_e32 v3, v12, v12
	v_floor_f32_e32 v3, v3
	v_add_u32_e32 v2, 0x80, v2
	v_cvt_i32_f32_e32 v3, v3
	v_min_u32_e32 v2, 0xff, v2
	v_cndmask_b32_e64 v2, v2, v226, s[18:19]
	v_lshl_add_u32 v2, v2, 2, s6
	ds_add_u32 v2, v223
	v_max_i32_e32 v2, 0xffffff80, v3
	s_waitcnt vmcnt(19)
	v_add_f32_e32 v3, v13, v13
	v_floor_f32_e32 v3, v3
	v_add_u32_e32 v2, 0x80, v2
	v_cvt_i32_f32_e32 v3, v3
	v_min_u32_e32 v2, 0xff, v2
	v_cndmask_b32_e64 v2, v2, v226, s[4:5]
	v_lshl_add_u32 v2, v2, 2, s6
	ds_add_u32 v2, v223
	v_max_i32_e32 v2, 0xffffff80, v3
	s_waitcnt vmcnt(18)
	v_add_f32_e32 v3, v14, v14
	v_floor_f32_e32 v3, v3
	v_add_u32_e32 v2, 0x80, v2
	v_cvt_i32_f32_e32 v3, v3
	v_min_u32_e32 v2, 0xff, v2
	v_cndmask_b32_e64 v2, v2, v226, s[10:11]
	v_lshl_add_u32 v2, v2, 2, s6
	ds_add_u32 v2, v223
	v_max_i32_e32 v2, 0xffffff80, v3
	s_waitcnt vmcnt(17)
	v_add_f32_e32 v3, v15, v15
	v_floor_f32_e32 v3, v3
	v_add_u32_e32 v2, 0x80, v2
	v_cvt_i32_f32_e32 v3, v3
	v_min_u32_e32 v2, 0xff, v2
	v_cndmask_b32_e64 v2, v2, v226, s[24:25]
	v_lshl_add_u32 v2, v2, 2, s6
	ds_add_u32 v2, v223
	v_max_i32_e32 v2, 0xffffff80, v3
	s_waitcnt vmcnt(16)
	v_add_f32_e32 v3, v16, v16
	v_floor_f32_e32 v3, v3
	v_add_u32_e32 v2, 0x80, v2
	v_cvt_i32_f32_e32 v3, v3
	v_min_u32_e32 v2, 0xff, v2
	v_cndmask_b32_e64 v2, v2, v226, s[26:27]
	v_lshl_add_u32 v2, v2, 2, s6
	ds_add_u32 v2, v223
	v_max_i32_e32 v2, 0xffffff80, v3
	s_waitcnt vmcnt(15)
	v_add_f32_e32 v3, v17, v17
	v_floor_f32_e32 v3, v3
	v_add_u32_e32 v2, 0x80, v2
	v_cvt_i32_f32_e32 v3, v3
	v_min_u32_e32 v2, 0xff, v2
	v_cndmask_b32_e64 v2, v2, v226, s[28:29]
	v_lshl_add_u32 v2, v2, 2, s6
	ds_add_u32 v2, v223
	v_max_i32_e32 v2, 0xffffff80, v3
	s_waitcnt vmcnt(14)
	v_add_f32_e32 v3, v18, v18
	v_floor_f32_e32 v3, v3
	v_add_u32_e32 v2, 0x80, v2
	v_cvt_i32_f32_e32 v3, v3
	v_min_u32_e32 v2, 0xff, v2
	v_cndmask_b32_e64 v2, v2, v226, s[30:31]
	v_lshl_add_u32 v2, v2, 2, s6
	ds_add_u32 v2, v223
	v_max_i32_e32 v2, 0xffffff80, v3
	s_waitcnt vmcnt(13)
	v_add_f32_e32 v3, v19, v19
	v_floor_f32_e32 v3, v3
	v_add_u32_e32 v2, 0x80, v2
	v_cvt_i32_f32_e32 v3, v3
	v_min_u32_e32 v2, 0xff, v2
	v_cndmask_b32_e64 v2, v2, v226, s[34:35]
	v_lshl_add_u32 v2, v2, 2, s6
	ds_add_u32 v2, v223
	v_max_i32_e32 v2, 0xffffff80, v3
	s_waitcnt vmcnt(12)
	v_add_f32_e32 v3, v20, v20
	v_floor_f32_e32 v3, v3
	v_add_u32_e32 v2, 0x80, v2
	v_cvt_i32_f32_e32 v3, v3
	v_min_u32_e32 v2, 0xff, v2
	v_cndmask_b32_e64 v2, v2, v226, s[36:37]
	v_lshl_add_u32 v2, v2, 2, s6
	ds_add_u32 v2, v223
	v_max_i32_e32 v2, 0xffffff80, v3
	s_waitcnt vmcnt(11)
; #define LAS __attribute__((address_space(3)))
; template <int NJ>
; __device__ __forceinline__ void select_rows(const GAS float* sr0, GAS unsigned long long* mb0, LAS unsigned* hist, LAS unsigned* kbuf, int ntl, int lane) {
;     ...
;             __hip_atomic_fetch_add(hist + (ok ? bk : 256), 1u, __ATOMIC_RELAXED, __HIP_MEMORY_SCOPE_WORKGROUP);
;         }
;         __builtin_amdgcn_wave_barrier();
;         asm volatile("s_waitcnt lgkmcnt(0)" ::: "memory");
;         unsigned B, rem, C;
;         {
;             const u32x4 hv = *(const LAS u32x4*)(hist + 4 * lane);
;             const unsigned s4 = hv.x + hv.y + hv.z + hv.w;
;             unsigned S = s4;
; #pragma unroll
;             for (int off = 1; off < 64; off <<= 1) { const unsigned n = __shfl_down(S, off); if (lane + off < 64) S += n; }
;             const unsigned excl = S - s4;
;             const bool mine = (excl < 256u) && (256u <= S);
;             unsigned dl, above, cnt, c = excl;
;             if (c + hv.w >= 256u) { dl = 3; above = c; cnt = hv.w; } else { c += hv.w; if (c + hv.z >= 256u) { dl = 2; above = c; cnt = hv.z; } else { c += hv.z; if (c + hv.y >= 256u) { dl = 1; above = c; cnt = hv.y; } else { c += hv.y; dl = 0; above = c; cnt = hv.x; } } }
;             const unsigned long long bm = __ballot(mine);
;             const int src = bm ? (int)__builtin_ctzll(bm) : 0;
;             B = (unsigned)__builtin_amdgcn_readlane((int)(4 * lane + dl), src);
;             rem = 256u - (unsigned)__builtin_amdgcn_readlane((int)above, src);
;             C = (unsigned)__builtin_amdgcn_readlane((int)cnt, src);
	v_add_f32_e32 v3, v21, v21
	v_floor_f32_e32 v3, v3
	v_add_u32_e32 v2, 0x80, v2
	v_cvt_i32_f32_e32 v3, v3
	v_min_u32_e32 v2, 0xff, v2
	v_cndmask_b32_e64 v2, v2, v226, s[38:39]
	v_lshl_add_u32 v2, v2, 2, s6
	ds_add_u32 v2, v223
	v_max_i32_e32 v2, 0xffffff80, v3
	s_waitcnt vmcnt(10)
	v_add_f32_e32 v3, v22, v22
	v_floor_f32_e32 v3, v3
	v_add_u32_e32 v2, 0x80, v2
	v_cvt_i32_f32_e32 v3, v3
	v_min_u32_e32 v2, 0xff, v2
	v_cndmask_b32_e64 v2, v2, v226, s[40:41]
	v_lshl_add_u32 v2, v2, 2, s6
	ds_add_u32 v2, v223
	v_max_i32_e32 v2, 0xffffff80, v3
	s_waitcnt vmcnt(9)
	v_add_f32_e32 v3, v23, v23
	v_floor_f32_e32 v3, v3
	v_add_u32_e32 v2, 0x80, v2
	v_cvt_i32_f32_e32 v3, v3
	v_min_u32_e32 v2, 0xff, v2
	v_cndmask_b32_e64 v2, v2, v226, s[42:43]
	v_lshl_add_u32 v2, v2, 2, s6
	ds_add_u32 v2, v223
	v_max_i32_e32 v2, 0xffffff80, v3
	s_waitcnt vmcnt(8)
	v_add_f32_e32 v3, v24, v24
	v_floor_f32_e32 v3, v3
	v_add_u32_e32 v2, 0x80, v2
	v_cvt_i32_f32_e32 v3, v3
	v_min_u32_e32 v2, 0xff, v2
	v_cndmask_b32_e64 v2, v2, v226, s[44:45]
	v_lshl_add_u32 v2, v2, 2, s6
	ds_add_u32 v2, v223
	v_max_i32_e32 v2, 0xffffff80, v3
	s_waitcnt vmcnt(7)
	v_add_f32_e32 v3, v25, v25
	v_floor_f32_e32 v3, v3
	v_add_u32_e32 v2, 0x80, v2
	v_cvt_i32_f32_e32 v3, v3
	v_min_u32_e32 v2, 0xff, v2
	v_cndmask_b32_e64 v2, v2, v226, s[46:47]
	v_lshl_add_u32 v2, v2, 2, s6
	ds_add_u32 v2, v223
	v_max_i32_e32 v2, 0xffffff80, v3
	s_waitcnt vmcnt(6)
	v_add_f32_e32 v3, v26, v26
	v_floor_f32_e32 v3, v3
	v_add_u32_e32 v2, 0x80, v2
	v_cvt_i32_f32_e32 v3, v3
	v_min_u32_e32 v2, 0xff, v2
	v_cndmask_b32_e64 v2, v2, v226, s[48:49]
	v_lshl_add_u32 v2, v2, 2, s6
	ds_add_u32 v2, v223
	v_max_i32_e32 v2, 0xffffff80, v3
	s_waitcnt vmcnt(5)
	v_add_f32_e32 v3, v27, v27
	v_floor_f32_e32 v3, v3
	v_add_u32_e32 v2, 0x80, v2
	v_cvt_i32_f32_e32 v3, v3
	v_min_u32_e32 v2, 0xff, v2
	v_cndmask_b32_e64 v2, v2, v226, s[50:51]
	v_lshl_add_u32 v2, v2, 2, s6
	ds_add_u32 v2, v223
	v_max_i32_e32 v2, 0xffffff80, v3
	s_waitcnt vmcnt(4)
	v_add_f32_e32 v3, v28, v28
	v_floor_f32_e32 v3, v3
	v_add_u32_e32 v2, 0x80, v2
	v_cvt_i32_f32_e32 v3, v3
	v_min_u32_e32 v2, 0xff, v2
	v_cndmask_b32_e64 v2, v2, v226, s[52:53]
	v_lshl_add_u32 v2, v2, 2, s6
	ds_add_u32 v2, v223
	v_max_i32_e32 v2, 0xffffff80, v3
	s_waitcnt vmcnt(3)
	v_add_f32_e32 v3, v29, v29
	v_floor_f32_e32 v3, v3
	v_add_u32_e32 v2, 0x80, v2
	v_cvt_i32_f32_e32 v3, v3
	v_min_u32_e32 v2, 0xff, v2
	v_cndmask_b32_e64 v2, v2, v226, s[64:65]
	v_lshl_add_u32 v2, v2, 2, s6
	ds_add_u32 v2, v223
	v_max_i32_e32 v2, 0xffffff80, v3
	s_waitcnt vmcnt(2)
	v_add_f32_e32 v3, v30, v30
	v_floor_f32_e32 v3, v3
	v_add_u32_e32 v2, 0x80, v2
	v_cvt_i32_f32_e32 v3, v3
	v_min_u32_e32 v2, 0xff, v2
	v_cndmask_b32_e64 v2, v2, v226, s[66:67]
	v_lshl_add_u32 v2, v2, 2, s6
	ds_add_u32 v2, v223
	v_max_i32_e32 v2, 0xffffff80, v3
	s_waitcnt vmcnt(1)
	v_add_f32_e32 v3, v31, v31
	v_floor_f32_e32 v3, v3
	v_add_u32_e32 v2, 0x80, v2
	v_cvt_i32_f32_e32 v3, v3
	v_min_u32_e32 v2, 0xff, v2
	v_cndmask_b32_e64 v2, v2, v226, s[70:71]
	v_lshl_add_u32 v2, v2, 2, s6
	ds_add_u32 v2, v223
	v_max_i32_e32 v2, 0xffffff80, v3
	s_waitcnt vmcnt(0)
	v_add_f32_e32 v3, v32, v32
	v_floor_f32_e32 v3, v3
	v_add_u32_e32 v2, 0x80, v2
	v_cvt_i32_f32_e32 v3, v3
	v_min_u32_e32 v2, 0xff, v2
	v_cndmask_b32_e64 v2, v2, v226, s[72:73]
	v_lshl_add_u32 v2, v2, 2, s6
	ds_add_u32 v2, v223
	v_max_i32_e32 v2, 0xffffff80, v3
	v_add_u32_e32 v2, 0x80, v2
	v_min_u32_e32 v2, 0xff, v2
	v_cndmask_b32_e64 v2, v2, v226, s[76:77]
	v_lshl_add_u32 v2, v2, 2, s6
	ds_add_u32 v2, v223
	s_waitcnt lgkmcnt(0)
	ds_read_b128 v[2:5], v7
	v_readlane_b32 s0, v254, 33
	v_readlane_b32 s1, v254, 34
	s_waitcnt lgkmcnt(0)
	v_add_u32_e32 v34, v2, v3
	v_add3_u32 v35, v34, v4, v5
	v_mov_b32_e32 v34, v35
	s_nop 1
	v_add_u32_dpp v34, v34, v34 row_shr:1 row_mask:0xf bank_mask:0xf bound_ctrl:0
	s_nop 1
	v_add_u32_dpp v34, v34, v34 row_shr:2 row_mask:0xf bank_mask:0xf bound_ctrl:0
	s_nop 1
	v_add_u32_dpp v34, v34, v34 row_shr:4 row_mask:0xf bank_mask:0xf bound_ctrl:0
	s_nop 1
	v_add_u32_dpp v34, v34, v34 row_shr:8 row_mask:0xf bank_mask:0xf bound_ctrl:0
	s_nop 1
	v_add_u32_dpp v34, v34, v34 row_bcast:15 row_mask:0xa bank_mask:0xf
	s_nop 1
	v_add_u32_dpp v34, v34, v34 row_bcast:31 row_mask:0xc bank_mask:0xf
	s_nop 1
	v_readlane_b32 s0, v34, 63
	s_nop 1
	v_sub_u32_e32 v36, s0, v34
	v_add_u32_e32 v34, v36, v35
	v_mov_b32_e32 v35, v36
	v_add_u32_e32 v42, v35, v5
	v_cmp_gt_u32_e32 vcc, s63, v42
	v_mov_b32_e32 v36, 3
	v_mov_b32_e32 v37, v35
	s_and_saveexec_b64 s[0:1], vcc
	s_cbranch_execz .LBB0_539
	v_add_u32_e32 v5, v42, v4
	v_cmp_gt_u32_e32 vcc, s63, v5
	v_mov_b32_e32 v36, 2
	s_and_saveexec_b64 s[2:3], vcc
	v_add_u32_e32 v4, v5, v3
	s_movk_i32 s8, 0xff
	v_cmp_lt_u32_e32 vcc, s8, v4
	s_nop 1
	v_cndmask_b32_e64 v36, 0, 1, vcc
	v_cndmask_b32_e32 v42, v4, v5, vcc
	v_cndmask_b32_e32 v4, v2, v3, vcc
	s_or_b64 exec, exec, s[2:3]
	v_mov_b32_e32 v5, v4
	v_mov_b32_e32 v37, v42

; #define WL1(J) if constexpr (J < NJ) { const unsigned long long w_ = __ballot(key[J] >= tau); const unsigned wl_ = (unsigned)w_, wh_ = (unsigned)(w_ >> 32); \
;                 asm volatile("s_nop 3\n\tv_writelane_b32 %0, %2, " #J "\n\tv_writelane_b32 %1, %3, " #J : "+v"(mlo), "+v"(mhi) : "s"(wl_), "s"(wh_)); }
; template <int NJ>
; __device__ __forceinline__ void select_rows(const GAS float* sr0, GAS unsigned long long* mb0, LAS unsigned* hist, LAS unsigned* kbuf, int ntl, int lane) {
;     ...
;             unsigned t = (have && cgt < rem) ? mykey : 0xffffffffu;
; #pragma unroll
;             for (int o = 1; o < 64; o <<= 1) t = min(t, (unsigned)__shfl_xor((int)t, o));
;             tau = t;
;             const unsigned long long eqm = __ballot(have && mykey == tau);
;             cnteq = (unsigned)__popcll(eqm);
;             remf = rem - (unsigned)__builtin_amdgcn_readlane((int)cgt, eqm ? (int)__builtin_ctzll(eqm) : 0);
;             generic = cnteq > remf;
;         }
;         unsigned mlo = 0u, mhi = 0u;
;         if (!generic) {
;     ...
;             WL1(0) WL1(1) WL1(2) WL1(3) WL1(4) WL1(5) WL1(6) WL1(7) WL1(8) WL1(9) WL1(10) WL1(11) WL1(12) WL1(13) WL1(14) WL1(15)
;             WL1(16) WL1(17) WL1(18) WL1(19) WL1(20) WL1(21) WL1(22) WL1(23) WL1(24) WL1(25) WL1(26) WL1(27) WL1(28) WL1(29) WL1(30) WL1(31)
.LBB0_640:
	s_sub_i32 s2, 0x100, s54
	v_cmp_gt_u32_e64 s[0:1], s2, v3
	v_and_b32_e32 v33, 64, v224
	s_and_b64 s[0:1], vcc, s[0:1]
	v_add_u32_e32 v33, 64, v33
	v_xor_b32_e32 v34, 1, v224
	s_waitcnt lgkmcnt(0)
	v_cndmask_b32_e64 v5, -1, v2, s[0:1]
	s_nop 1
	v_min_u32_dpp v5, v5, v5 row_shr:1 row_mask:0xf bank_mask:0xf
	s_nop 1
	v_min_u32_dpp v5, v5, v5 row_shr:2 row_mask:0xf bank_mask:0xf
	s_nop 1
	v_min_u32_dpp v5, v5, v5 row_shr:4 row_mask:0xf bank_mask:0xf
	s_nop 1
	v_min_u32_dpp v5, v5, v5 row_shr:8 row_mask:0xf bank_mask:0xf
	s_nop 1
	v_min_u32_dpp v5, v5, v5 row_bcast:15 row_mask:0xa bank_mask:0xf
	s_nop 1
	v_min_u32_dpp v5, v5, v5 row_bcast:31 row_mask:0xc bank_mask:0xf
	s_nop 1
	v_readlane_b32 s0, v5, 63
	s_nop 1
	v_mov_b32_e32 v5, s0
	v_cmp_eq_u32_e64 s[0:1], v2, v5
	s_and_b64 s[0:1], vcc, s[0:1]
	s_nop 0
	v_cndmask_b32_e64 v2, 0, 1, s[0:1]
	v_cmp_ne_u32_e32 vcc, 0, v2
	s_bcnt1_i32_b64 s0, vcc
	s_ff1_i32_b64 s1, vcc
	s_cmp_lg_u64 vcc, 0
	s_cselect_b32 s1, s1, 0
	v_readlane_b32 s1, v3, s1
	s_sub_i32 s1, s2, s1
	s_cmp_ge_u32 s1, s0
	s_mov_b64 s[0:1], -1
	s_cbranch_scc0 .LBB0_642
	v_cmp_ge_u32_e32 vcc, v4, v5
	v_mov_b32_e32 v2, v0
	v_mov_b32_e32 v3, v0
	s_nop 3
	v_writelane_b32 v2, vcc_lo, 0
	v_writelane_b32 v3, vcc_hi, 0
	v_cmp_ge_u32_e32 vcc, v10, v5
	s_nop 3
	v_writelane_b32 v2, vcc_lo, 1
	v_writelane_b32 v3, vcc_hi, 1
	v_cmp_ge_u32_e32 vcc, v11, v5
	s_nop 3
	v_writelane_b32 v2, vcc_lo, 2
	v_writelane_b32 v3, vcc_hi, 2
	v_cmp_ge_u32_e32 vcc, v12, v5
	s_nop 3
	v_writelane_b32 v2, vcc_lo, 3
	v_writelane_b32 v3, vcc_hi, 3
	v_cmp_ge_u32_e32 vcc, v13, v5
	s_nop 3
	v_writelane_b32 v2, vcc_lo, 4
	v_writelane_b32 v3, vcc_hi, 4
	v_cmp_ge_u32_e32 vcc, v14, v5
	s_nop 3
	v_writelane_b32 v2, vcc_lo, 5
	v_writelane_b32 v3, vcc_hi, 5
	v_cmp_ge_u32_e32 vcc, v15, v5
	s_nop 3
	v_writelane_b32 v2, vcc_lo, 6
	v_writelane_b32 v3, vcc_hi, 6
	v_cmp_ge_u32_e32 vcc, v16, v5
	s_nop 3
	v_writelane_b32 v2, vcc_lo, 7
	v_writelane_b32 v3, vcc_hi, 7
	v_cmp_ge_u32_e32 vcc, v17, v5
	s_nop 3
	v_writelane_b32 v2, vcc_lo, 8
	v_writelane_b32 v3, vcc_hi, 8
	v_cmp_ge_u32_e32 vcc, v18, v5
	s_nop 3
	v_writelane_b32 v2, vcc_lo, 9
	v_writelane_b32 v3, vcc_hi, 9
	v_cmp_ge_u32_e32 vcc, v19, v5
	s_nop 3
	v_writelane_b32 v2, vcc_lo, 10
	v_writelane_b32 v3, vcc_hi, 10
	v_cmp_ge_u32_e32 vcc, v20, v5
	s_nop 3
	v_writelane_b32 v2, vcc_lo, 11
	v_writelane_b32 v3, vcc_hi, 11
	v_cmp_ge_u32_e32 vcc, v21, v5
	s_nop 3
	v_writelane_b32 v2, vcc_lo, 12
	v_writelane_b32 v3, vcc_hi, 12
	v_cmp_ge_u32_e32 vcc, v22, v5
	s_nop 3
	v_writelane_b32 v2, vcc_lo, 13
	v_writelane_b32 v3, vcc_hi, 13
	v_cmp_ge_u32_e32 vcc, v23, v5
	s_nop 3
	v_writelane_b32 v2, vcc_lo, 14
	v_writelane_b32 v3, vcc_hi, 14
	v_cmp_ge_u32_e32 vcc, v24, v5
	s_nop 3
	v_writelane_b32 v2, vcc_lo, 15
	v_writelane_b32 v3, vcc_hi, 15
	v_cmp_ge_u32_e32 vcc, v25, v5
	s_nop 3
	v_writelane_b32 v2, vcc_lo, 16
	v_writelane_b32 v3, vcc_hi, 16
	v_cmp_ge_u32_e32 vcc, v26, v5
	s_nop 3
	v_writelane_b32 v2, vcc_lo, 17
	v_writelane_b32 v3, vcc_hi, 17
	v_cmp_ge_u32_e32 vcc, v27, v5
	s_nop 3
	v_writelane_b32 v2, vcc_lo, 18
	v_writelane_b32 v3, vcc_hi, 18
	v_cmp_ge_u32_e32 vcc, v28, v5
	s_nop 3
	v_writelane_b32 v2, vcc_lo, 19
	v_writelane_b32 v3, vcc_hi, 19
	v_cmp_ge_u32_e32 vcc, v29, v5
	s_nop 3
	v_writelane_b32 v2, vcc_lo, 20
	v_writelane_b32 v3, vcc_hi, 20
	v_cmp_ge_u32_e32 vcc, v30, v5
	s_nop 3
	v_writelane_b32 v2, vcc_lo, 21
	v_writelane_b32 v3, vcc_hi, 21
	v_cmp_ge_u32_e32 vcc, v31, v5
	s_nop 3
	v_writelane_b32 v2, vcc_lo, 22
	v_writelane_b32 v3, vcc_hi, 22
	v_cmp_ge_u32_e32 vcc, v32, v5
	s_nop 3
	v_writelane_b32 v2, vcc_lo, 23
	v_writelane_b32 v3, vcc_hi, 23
	s_mov_b64 s[0:1], 0

; #define LAS __attribute__((address_space(3)))
; #define GAS __attribute__((address_space(1)))
; template <int NJ>
; __device__ __forceinline__ void select_rows(const GAS float* sr0, GAS unsigned long long* mb0, LAS unsigned* hist, LAS unsigned* kbuf, int ntl, int lane) {
;     ...
;     for (int rr = 0; rr < 8; ++rr) {
;         const GAS float* srow = sr0 + (size_t)rr * SEQ;
;         float fv[NJ];
; #pragma unroll
;         for (int j = 0; j < NJ; ++j) fv[j] = srow[64 * j];
;         { unsigned z = 0u; asm volatile("" : "+v"(z));
;           *(LAS u32x4*)(hist + 4 * lane) = (u32x4){z, z, z, z}; if (lane < 2) hist[256 + lane] = z; }
;         __builtin_amdgcn_wave_barrier();
;         unsigned key[NJ];
; #pragma unroll
;         for (int j = 0; j < NJ; ++j) {
;             const float f = fv[j]; const bool ok = (vm >> j) & 1u;
;             key[j] = ok ? skey_of(f) : 0u;
;             const int bk = min(max((int)floorf(f + f) + 128, 0), 255);
;             __hip_atomic_fetch_add(hist + (ok ? bk : 256), 1u, __ATOMIC_RELAXED, __HIP_MEMORY_SCOPE_WORKGROUP);
;         }
;         __builtin_amdgcn_wave_barrier();
;         asm volatile("s_waitcnt lgkmcnt(0)" ::: "memory");
;         unsigned B, rem, C;
;         {
;             const u32x4 hv = *(const LAS u32x4*)(hist + 4 * lane);
;             const unsigned s4 = hv.x + hv.y + hv.z + hv.w;
;             unsigned S = s4;
; #pragma unroll
;             for (int off = 1; off < 64; off <<= 1) { const unsigned n = __shfl_down(S, off); if (lane + off < 64) S += n; }
;             const unsigned excl = S - s4;
;             const bool mine = (excl < 256u) && (256u <= S);
;             unsigned dl, above, cnt, c = excl;
;             if (c + hv.w >= 256u) { dl = 3; above = c; cnt = hv.w; } else { c += hv.w; if (c + hv.z >= 256u) { dl = 2; above = c; cnt = hv.z; } else { c += hv.z; if (c + hv.y >= 256u) { dl = 1; above = c; cnt = hv.y; } else { c += hv.y; dl = 0; above = c; cnt = hv.x; } } }
;             const unsigned long long bm = __ballot(mine);
;             const int src = bm ? (int)__builtin_ctzll(bm) : 0;
;             B = (unsigned)__builtin_amdgcn_readlane((int)(4 * lane + dl), src);
;             rem = 256u - (unsigned)__builtin_amdgcn_readlane((int)above, src);
;             C = (unsigned)__builtin_amdgcn_readlane((int)cnt, src);
.LBB0_652:
	s_lshl_b32 s88, s7, 11
	v_lshl_add_u64 v[2:3], s[88:89], 2, v[8:9]
	global_load_dword v25, v[2:3], off
	global_load_dword v10, v[2:3], off offset:256
	global_load_dword v11, v[2:3], off offset:512
	global_load_dword v12, v[2:3], off offset:768
	global_load_dword v13, v[2:3], off offset:1024
	global_load_dword v14, v[2:3], off offset:1280
	global_load_dword v15, v[2:3], off offset:1536
	global_load_dword v16, v[2:3], off offset:1792
	global_load_dword v17, v[2:3], off offset:2048
	global_load_dword v18, v[2:3], off offset:2304
	global_load_dword v19, v[2:3], off offset:2560
	global_load_dword v20, v[2:3], off offset:2816
	global_load_dword v21, v[2:3], off offset:3072
	global_load_dword v22, v[2:3], off offset:3328
	global_load_dword v23, v[2:3], off offset:3584
	global_load_dword v24, v[2:3], off offset:3840
	v_mov_b32_e32 v2, 0
	s_nop 0
	v_mov_b32_e32 v3, v2
	v_mov_b32_e32 v4, v2
	v_mov_b32_e32 v5, v2
	ds_write_b128 v7, v[2:5]
	s_mov_b64 s[8:9], exec
	v_readlane_b32 s38, v254, 15
	v_readlane_b32 s39, v254, 16
	s_and_b64 s[38:39], s[8:9], s[38:39]
	s_mov_b64 exec, s[38:39]
	v_add_u32_e32 v3, v7, v38
	ds_write_b32 v3, v2 offset:1024
	s_or_b64 exec, exec, s[8:9]
	s_waitcnt vmcnt(15)
	v_add_f32_e32 v2, v25, v25
	v_floor_f32_e32 v2, v2
	v_cvt_i32_f32_e32 v2, v2
	s_waitcnt vmcnt(14)
	v_add_f32_e32 v3, v10, v10
	v_floor_f32_e32 v3, v3
	v_cvt_i32_f32_e32 v3, v3
	v_max_i32_e32 v2, 0xffffff80, v2
	v_add_u32_e32 v2, 0x80, v2
	v_min_u32_e32 v2, 0xff, v2
	v_cndmask_b32_e64 v2, v2, v226, s[0:1]
	v_lshl_add_u32 v2, v2, 2, s6
	ds_add_u32 v2, v223
	v_max_i32_e32 v2, 0xffffff80, v3
	s_waitcnt vmcnt(13)
	v_add_f32_e32 v3, v11, v11
	v_floor_f32_e32 v3, v3
	v_add_u32_e32 v2, 0x80, v2
	v_cvt_i32_f32_e32 v3, v3
	v_min_u32_e32 v2, 0xff, v2
	v_cndmask_b32_e64 v2, v2, v226, s[2:3]
	v_lshl_add_u32 v2, v2, 2, s6
	ds_add_u32 v2, v223
	v_max_i32_e32 v2, 0xffffff80, v3
	s_waitcnt vmcnt(12)
	v_add_f32_e32 v3, v12, v12
	v_floor_f32_e32 v3, v3
	v_add_u32_e32 v2, 0x80, v2
	v_cvt_i32_f32_e32 v3, v3
	v_min_u32_e32 v2, 0xff, v2
	v_cndmask_b32_e64 v2, v2, v226, s[4:5]
	v_lshl_add_u32 v2, v2, 2, s6
	ds_add_u32 v2, v223
	v_max_i32_e32 v2, 0xffffff80, v3
	s_waitcnt vmcnt(11)
	v_add_f32_e32 v3, v13, v13
	v_floor_f32_e32 v3, v3
	v_add_u32_e32 v2, 0x80, v2
	v_cvt_i32_f32_e32 v3, v3
	v_min_u32_e32 v2, 0xff, v2
	v_cndmask_b32_e64 v2, v2, v226, s[10:11]
	v_lshl_add_u32 v2, v2, 2, s6
	ds_add_u32 v2, v223
	v_max_i32_e32 v2, 0xffffff80, v3
	s_waitcnt vmcnt(10)
	v_add_f32_e32 v3, v14, v14
	v_floor_f32_e32 v3, v3
	v_add_u32_e32 v2, 0x80, v2
	v_cvt_i32_f32_e32 v3, v3
	v_min_u32_e32 v2, 0xff, v2
	v_cndmask_b32_e64 v2, v2, v226, s[12:13]
	v_lshl_add_u32 v2, v2, 2, s6
	ds_add_u32 v2, v223
	v_max_i32_e32 v2, 0xffffff80, v3
	s_waitcnt vmcnt(9)
	v_add_f32_e32 v3, v15, v15
	v_floor_f32_e32 v3, v3
	v_add_u32_e32 v2, 0x80, v2
	v_cvt_i32_f32_e32 v3, v3
	v_min_u32_e32 v2, 0xff, v2
	v_cndmask_b32_e64 v2, v2, v226, s[14:15]
	v_lshl_add_u32 v2, v2, 2, s6
	ds_add_u32 v2, v223
	v_max_i32_e32 v2, 0xffffff80, v3
	s_waitcnt vmcnt(8)
	v_add_f32_e32 v3, v16, v16
	v_floor_f32_e32 v3, v3
	v_add_u32_e32 v2, 0x80, v2
	v_cvt_i32_f32_e32 v3, v3
	v_min_u32_e32 v2, 0xff, v2
	v_cndmask_b32_e64 v2, v2, v226, s[16:17]
	v_lshl_add_u32 v2, v2, 2, s6
	ds_add_u32 v2, v223
	v_max_i32_e32 v2, 0xffffff80, v3
	s_waitcnt vmcnt(7)
	v_add_f32_e32 v3, v17, v17
	v_floor_f32_e32 v3, v3
	v_add_u32_e32 v2, 0x80, v2
	v_cvt_i32_f32_e32 v3, v3
	v_min_u32_e32 v2, 0xff, v2
	v_cndmask_b32_e64 v2, v2, v226, s[18:19]
	v_lshl_add_u32 v2, v2, 2, s6
	ds_add_u32 v2, v223
	v_max_i32_e32 v2, 0xffffff80, v3
	s_waitcnt vmcnt(6)
	v_add_f32_e32 v3, v18, v18
	v_floor_f32_e32 v3, v3
	v_add_u32_e32 v2, 0x80, v2
	v_cvt_i32_f32_e32 v3, v3
	v_min_u32_e32 v2, 0xff, v2
	v_cndmask_b32_e64 v2, v2, v226, s[52:53]
	v_lshl_add_u32 v2, v2, 2, s6
	ds_add_u32 v2, v223
	v_max_i32_e32 v2, 0xffffff80, v3
	s_waitcnt vmcnt(5)
	v_add_f32_e32 v3, v19, v19
	v_floor_f32_e32 v3, v3
	v_add_u32_e32 v2, 0x80, v2
	v_cvt_i32_f32_e32 v3, v3
	v_min_u32_e32 v2, 0xff, v2
	v_cndmask_b32_e64 v2, v2, v226, s[54:55]
	v_lshl_add_u32 v2, v2, 2, s6
	ds_add_u32 v2, v223
	v_max_i32_e32 v2, 0xffffff80, v3
	s_waitcnt vmcnt(4)
	v_add_f32_e32 v3, v20, v20
	v_floor_f32_e32 v3, v3
	v_add_u32_e32 v2, 0x80, v2
	v_cvt_i32_f32_e32 v3, v3
	v_min_u32_e32 v2, 0xff, v2
	v_cndmask_b32_e64 v2, v2, v226, s[24:25]
	v_lshl_add_u32 v2, v2, 2, s6
	ds_add_u32 v2, v223
	v_max_i32_e32 v2, 0xffffff80, v3
	s_waitcnt vmcnt(3)
	v_add_f32_e32 v3, v21, v21
	v_floor_f32_e32 v3, v3
	v_add_u32_e32 v2, 0x80, v2
	v_cvt_i32_f32_e32 v3, v3
	v_min_u32_e32 v2, 0xff, v2
	v_cndmask_b32_e64 v2, v2, v226, s[26:27]
	v_lshl_add_u32 v2, v2, 2, s6
	ds_add_u32 v2, v223
	v_max_i32_e32 v2, 0xffffff80, v3
	s_waitcnt vmcnt(2)
	v_add_f32_e32 v3, v22, v22
	v_floor_f32_e32 v3, v3
	v_add_u32_e32 v2, 0x80, v2
	v_cvt_i32_f32_e32 v3, v3
	v_min_u32_e32 v2, 0xff, v2
	v_cndmask_b32_e64 v2, v2, v226, s[28:29]
	v_lshl_add_u32 v2, v2, 2, s6
	ds_add_u32 v2, v223
	v_max_i32_e32 v2, 0xffffff80, v3
	s_waitcnt vmcnt(1)
	v_add_f32_e32 v3, v23, v23
	v_floor_f32_e32 v3, v3
	v_add_u32_e32 v2, 0x80, v2
	v_cvt_i32_f32_e32 v3, v3
	v_min_u32_e32 v2, 0xff, v2
	v_cndmask_b32_e64 v2, v2, v226, s[30:31]
	v_lshl_add_u32 v2, v2, 2, s6
	ds_add_u32 v2, v223
	v_max_i32_e32 v2, 0xffffff80, v3
	s_waitcnt vmcnt(0)
	v_add_f32_e32 v3, v24, v24
	v_floor_f32_e32 v3, v3
	v_add_u32_e32 v2, 0x80, v2
	v_cvt_i32_f32_e32 v3, v3
	v_min_u32_e32 v2, 0xff, v2
	v_cndmask_b32_e64 v2, v2, v226, s[34:35]
	v_lshl_add_u32 v2, v2, 2, s6
	ds_add_u32 v2, v223
	v_max_i32_e32 v2, 0xffffff80, v3
	v_add_u32_e32 v2, 0x80, v2
	v_min_u32_e32 v2, 0xff, v2
	v_cndmask_b32_e64 v2, v2, v226, s[36:37]
	v_lshl_add_u32 v2, v2, 2, s6
	ds_add_u32 v2, v223
	s_waitcnt lgkmcnt(0)
	ds_read_b128 v[2:5], v7
	v_readlane_b32 s8, v254, 12
	v_readlane_b32 s9, v254, 13
	s_waitcnt lgkmcnt(0)
	v_add_u32_e32 v26, v2, v3
	v_add3_u32 v27, v26, v4, v5
	v_mov_b32_e32 v26, v27
	s_nop 1
	v_add_u32_dpp v26, v26, v26 row_shr:1 row_mask:0xf bank_mask:0xf bound_ctrl:0
	s_nop 1
	v_add_u32_dpp v26, v26, v26 row_shr:2 row_mask:0xf bank_mask:0xf bound_ctrl:0
	s_nop 1
	v_add_u32_dpp v26, v26, v26 row_shr:4 row_mask:0xf bank_mask:0xf bound_ctrl:0
	s_nop 1
	v_add_u32_dpp v26, v26, v26 row_shr:8 row_mask:0xf bank_mask:0xf bound_ctrl:0
	s_nop 1
	v_add_u32_dpp v26, v26, v26 row_bcast:15 row_mask:0xa bank_mask:0xf
	s_nop 1
	v_add_u32_dpp v26, v26, v26 row_bcast:31 row_mask:0xc bank_mask:0xf
	s_nop 1
	v_readlane_b32 s8, v26, 63
	s_nop 1
	v_sub_u32_e32 v28, s8, v26
	v_add_u32_e32 v26, v28, v27
	v_mov_b32_e32 v27, v28
	v_add_u32_e32 v30, v27, v5
	v_cmp_gt_u32_e32 vcc, s63, v30
	v_mov_b32_e32 v28, 3
	v_mov_b32_e32 v29, v27
	s_and_saveexec_b64 s[8:9], vcc
	s_mov_b32 s88, 0xefa18f08
	s_cbranch_execz .LBB0_658
; template <int NJ>
; __device__ __forceinline__ void select_rows(const GAS float* sr0, GAS unsigned long long* mb0, LAS unsigned* hist, LAS unsigned* kbuf, int ntl, int lane) {
;     ...
;             unsigned dl, above, cnt, c = excl;
;             if (c + hv.w >= 256u) { dl = 3; above = c; cnt = hv.w; } else { c += hv.w; if (c + hv.z >= 256u) { dl = 2; above = c; cnt = hv.z; } else { c += hv.z; if (c + hv.y >= 256u) { dl = 1; above = c; cnt = hv.y; } else { c += hv.y; dl = 0; above = c; cnt = hv.x; } } }
;             const unsigned long long bm = __ballot(mine);
;             const int src = bm ? (int)__builtin_ctzll(bm) : 0;
;             B = (unsigned)__builtin_amdgcn_readlane((int)(4 * lane + dl), src);
;             rem = 256u - (unsigned)__builtin_amdgcn_readlane((int)above, src);
;             C = (unsigned)__builtin_amdgcn_readlane((int)cnt, src);
	v_add_u32_e32 v5, v30, v4
	v_cmp_gt_u32_e32 vcc, s63, v5
	v_mov_b32_e32 v28, 2
	s_and_saveexec_b64 s[38:39], vcc
	v_add_u32_e32 v4, v5, v3
	s_movk_i32 s40, 0xff
	v_cmp_lt_u32_e32 vcc, s40, v4
	s_nop 1
	v_cndmask_b32_e64 v28, 0, 1, vcc
	v_cndmask_b32_e32 v30, v4, v5, vcc
	v_cndmask_b32_e32 v4, v2, v3, vcc
	s_or_b64 exec, exec, s[38:39]
	v_mov_b32_e32 v5, v4
	v_mov_b32_e32 v29, v30

; #define WL1(J) if constexpr (J < NJ) { const unsigned long long w_ = __ballot(key[J] >= tau); const unsigned wl_ = (unsigned)w_, wh_ = (unsigned)(w_ >> 32); \
;                 asm volatile("s_nop 3\n\tv_writelane_b32 %0, %2, " #J "\n\tv_writelane_b32 %1, %3, " #J : "+v"(mlo), "+v"(mhi) : "s"(wl_), "s"(wh_)); }
; template <int NJ>
; __device__ __forceinline__ void select_rows(const GAS float* sr0, GAS unsigned long long* mb0, LAS unsigned* hist, LAS unsigned* kbuf, int ntl, int lane) {
;     ...
;             unsigned t = (have && cgt < rem) ? mykey : 0xffffffffu;
; #pragma unroll
;             for (int o = 1; o < 64; o <<= 1) t = min(t, (unsigned)__shfl_xor((int)t, o));
;             tau = t;
;             const unsigned long long eqm = __ballot(have && mykey == tau);
;             cnteq = (unsigned)__popcll(eqm);
;             remf = rem - (unsigned)__builtin_amdgcn_readlane((int)cgt, eqm ? (int)__builtin_ctzll(eqm) : 0);
;             generic = cnteq > remf;
;         }
;         unsigned mlo = 0u, mhi = 0u;
;         if (!generic) {
;     ...
;             WL1(0) WL1(1) WL1(2) WL1(3) WL1(4) WL1(5) WL1(6) WL1(7) WL1(8) WL1(9) WL1(10) WL1(11) WL1(12) WL1(13) WL1(14) WL1(15)
;             WL1(16) WL1(17) WL1(18) WL1(19) WL1(20) WL1(21) WL1(22) WL1(23) WL1(24) WL1(25) WL1(26) WL1(27) WL1(28) WL1(29) WL1(30) WL1(31)
.LBB0_727:
	s_sub_i32 s38, 0x100, s42
	v_cmp_gt_u32_e64 s[8:9], s38, v3
	v_and_b32_e32 v25, 64, v224
	s_and_b64 s[8:9], vcc, s[8:9]
	v_add_u32_e32 v25, 64, v25
	v_xor_b32_e32 v26, 1, v224
	s_waitcnt lgkmcnt(0)
	v_cndmask_b32_e64 v5, -1, v2, s[8:9]
	s_nop 1
	v_min_u32_dpp v5, v5, v5 row_shr:1 row_mask:0xf bank_mask:0xf
	s_nop 1
	v_min_u32_dpp v5, v5, v5 row_shr:2 row_mask:0xf bank_mask:0xf
	s_nop 1
	v_min_u32_dpp v5, v5, v5 row_shr:4 row_mask:0xf bank_mask:0xf
	s_nop 1
	v_min_u32_dpp v5, v5, v5 row_shr:8 row_mask:0xf bank_mask:0xf
	s_nop 1
	v_min_u32_dpp v5, v5, v5 row_bcast:15 row_mask:0xa bank_mask:0xf
	s_nop 1
	v_min_u32_dpp v5, v5, v5 row_bcast:31 row_mask:0xc bank_mask:0xf
	s_nop 1
	v_readlane_b32 s8, v5, 63
	s_nop 1
	v_mov_b32_e32 v5, s8
	v_cmp_eq_u32_e64 s[8:9], v2, v5
	s_and_b64 s[8:9], vcc, s[8:9]
	s_nop 0
	v_cndmask_b32_e64 v2, 0, 1, s[8:9]
	v_cmp_ne_u32_e32 vcc, 0, v2
	s_bcnt1_i32_b64 s8, vcc
	s_ff1_i32_b64 s9, vcc
	s_cmp_lg_u64 vcc, 0
	s_cselect_b32 s9, s9, 0
	v_readlane_b32 s9, v3, s9
	s_sub_i32 s9, s38, s9
	s_cmp_ge_u32 s9, s8
	s_mov_b64 s[8:9], -1
	s_cbranch_scc0 .LBB0_729
	v_cmp_ge_u32_e32 vcc, v4, v5
	v_mov_b32_e32 v2, v0
	v_mov_b32_e32 v3, v0
	s_nop 3
	v_writelane_b32 v2, vcc_lo, 0
	v_writelane_b32 v3, vcc_hi, 0
	v_cmp_ge_u32_e32 vcc, v10, v5
	s_nop 3
	v_writelane_b32 v2, vcc_lo, 1
	v_writelane_b32 v3, vcc_hi, 1
	v_cmp_ge_u32_e32 vcc, v11, v5
	s_nop 3
	v_writelane_b32 v2, vcc_lo, 2
	v_writelane_b32 v3, vcc_hi, 2
	v_cmp_ge_u32_e32 vcc, v12, v5
	s_nop 3
	v_writelane_b32 v2, vcc_lo, 3
	v_writelane_b32 v3, vcc_hi, 3
	v_cmp_ge_u32_e32 vcc, v13, v5
	s_nop 3
	v_writelane_b32 v2, vcc_lo, 4
	v_writelane_b32 v3, vcc_hi, 4
	v_cmp_ge_u32_e32 vcc, v14, v5
	s_nop 3
	v_writelane_b32 v2, vcc_lo, 5
	v_writelane_b32 v3, vcc_hi, 5
	v_cmp_ge_u32_e32 vcc, v15, v5
	s_nop 3
	v_writelane_b32 v2, vcc_lo, 6
	v_writelane_b32 v3, vcc_hi, 6
	v_cmp_ge_u32_e32 vcc, v16, v5
	s_nop 3
	v_writelane_b32 v2, vcc_lo, 7
	v_writelane_b32 v3, vcc_hi, 7
	v_cmp_ge_u32_e32 vcc, v17, v5
	s_nop 3
	v_writelane_b32 v2, vcc_lo, 8
	v_writelane_b32 v3, vcc_hi, 8
	v_cmp_ge_u32_e32 vcc, v18, v5
	s_nop 3
	v_writelane_b32 v2, vcc_lo, 9
	v_writelane_b32 v3, vcc_hi, 9
	v_cmp_ge_u32_e32 vcc, v19, v5
	s_nop 3
	v_writelane_b32 v2, vcc_lo, 10
	v_writelane_b32 v3, vcc_hi, 10
	v_cmp_ge_u32_e32 vcc, v20, v5
	s_nop 3
	v_writelane_b32 v2, vcc_lo, 11
	v_writelane_b32 v3, vcc_hi, 11
	v_cmp_ge_u32_e32 vcc, v21, v5
	s_nop 3
	v_writelane_b32 v2, vcc_lo, 12
	v_writelane_b32 v3, vcc_hi, 12
	v_cmp_ge_u32_e32 vcc, v22, v5
	s_nop 3
	v_writelane_b32 v2, vcc_lo, 13
	v_writelane_b32 v3, vcc_hi, 13
	v_cmp_ge_u32_e32 vcc, v23, v5
	s_nop 3
	v_writelane_b32 v2, vcc_lo, 14
	v_writelane_b32 v3, vcc_hi, 14
	v_cmp_ge_u32_e32 vcc, v24, v5
	s_nop 3
	v_writelane_b32 v2, vcc_lo, 15
	v_writelane_b32 v3, vcc_hi, 15
	s_mov_b64 s[8:9], 0

; #define LAS __attribute__((address_space(3)))
; #define GAS __attribute__((address_space(1)))
; template <int NJ>
; __device__ __forceinline__ void select_rows(const GAS float* sr0, GAS unsigned long long* mb0, LAS unsigned* hist, LAS unsigned* kbuf, int ntl, int lane) {
;     ...
;     for (int rr = 0; rr < 8; ++rr) {
;         const GAS float* srow = sr0 + (size_t)rr * SEQ;
;         float fv[NJ];
; #pragma unroll
;         for (int j = 0; j < NJ; ++j) fv[j] = srow[64 * j];
;         { unsigned z = 0u; asm volatile("" : "+v"(z));
;           *(LAS u32x4*)(hist + 4 * lane) = (u32x4){z, z, z, z}; if (lane < 2) hist[256 + lane] = z; }
;         __builtin_amdgcn_wave_barrier();
;         unsigned key[NJ];
; #pragma unroll
;         for (int j = 0; j < NJ; ++j) {
;             const float f = fv[j]; const bool ok = (vm >> j) & 1u;
;             key[j] = ok ? skey_of(f) : 0u;
;             const int bk = min(max((int)floorf(f + f) + 128, 0), 255);
;             __hip_atomic_fetch_add(hist + (ok ? bk : 256), 1u, __ATOMIC_RELAXED, __HIP_MEMORY_SCOPE_WORKGROUP);
;         }
;         __builtin_amdgcn_wave_barrier();
;         asm volatile("s_waitcnt lgkmcnt(0)" ::: "memory");
;         unsigned B, rem, C;
;         {
;             const u32x4 hv = *(const LAS u32x4*)(hist + 4 * lane);
;             const unsigned s4 = hv.x + hv.y + hv.z + hv.w;
;             unsigned S = s4;
; #pragma unroll
;             for (int off = 1; off < 64; off <<= 1) { const unsigned n = __shfl_down(S, off); if (lane + off < 64) S += n; }
;             const unsigned excl = S - s4;
;             const bool mine = (excl < 256u) && (256u <= S);
;             unsigned dl, above, cnt, c = excl;
;             if (c + hv.w >= 256u) { dl = 3; above = c; cnt = hv.w; } else { c += hv.w; if (c + hv.z >= 256u) { dl = 2; above = c; cnt = hv.z; } else { c += hv.z; if (c + hv.y >= 256u) { dl = 1; above = c; cnt = hv.y; } else { c += hv.y; dl = 0; above = c; cnt = hv.x; } } }
;             const unsigned long long bm = __ballot(mine);
;             const int src = bm ? (int)__builtin_ctzll(bm) : 0;
;             B = (unsigned)__builtin_amdgcn_readlane((int)(4 * lane + dl), src);
;             rem = 256u - (unsigned)__builtin_amdgcn_readlane((int)above, src);
;             C = (unsigned)__builtin_amdgcn_readlane((int)cnt, src);
.LBB0_739:
	s_lshl_b32 s88, s7, 11
	v_lshl_add_u64 v[2:3], s[88:89], 2, v[8:9]
	global_load_dword v17, v[2:3], off
	global_load_dword v10, v[2:3], off offset:256
	global_load_dword v11, v[2:3], off offset:512
	global_load_dword v12, v[2:3], off offset:768
	global_load_dword v13, v[2:3], off offset:1024
	global_load_dword v14, v[2:3], off offset:1280
	global_load_dword v15, v[2:3], off offset:1536
	global_load_dword v16, v[2:3], off offset:1792
	v_mov_b32_e32 v2, 0
	s_nop 0
	v_mov_b32_e32 v3, v2
	v_mov_b32_e32 v4, v2
	v_mov_b32_e32 v5, v2
	ds_write_b128 v7, v[2:5]
	s_and_saveexec_b64 s[8:9], s[74:75]
	v_add_u32_e32 v3, v7, v38
	ds_write_b32 v3, v2 offset:1024
	s_or_b64 exec, exec, s[8:9]
	s_waitcnt vmcnt(7)
	v_add_f32_e32 v2, v17, v17
	v_floor_f32_e32 v2, v2
	v_cvt_i32_f32_e32 v2, v2
	s_waitcnt vmcnt(6)
	v_add_f32_e32 v3, v10, v10
	v_floor_f32_e32 v3, v3
	v_cvt_i32_f32_e32 v3, v3
	v_max_i32_e32 v2, 0xffffff80, v2
	v_add_u32_e32 v2, 0x80, v2
	v_min_u32_e32 v2, 0xff, v2
	v_cndmask_b32_e64 v2, v2, v226, s[0:1]
	v_lshl_add_u32 v2, v2, 2, s6
	ds_add_u32 v2, v223
	v_max_i32_e32 v2, 0xffffff80, v3
	s_waitcnt vmcnt(5)
	v_add_f32_e32 v3, v11, v11
	v_floor_f32_e32 v3, v3
	v_add_u32_e32 v2, 0x80, v2
	v_cvt_i32_f32_e32 v3, v3
	v_min_u32_e32 v2, 0xff, v2
	v_cndmask_b32_e64 v2, v2, v226, s[2:3]
	v_lshl_add_u32 v2, v2, 2, s6
	ds_add_u32 v2, v223
	v_max_i32_e32 v2, 0xffffff80, v3
	s_waitcnt vmcnt(4)
	v_add_f32_e32 v3, v12, v12
	v_floor_f32_e32 v3, v3
	v_add_u32_e32 v2, 0x80, v2
	v_cvt_i32_f32_e32 v3, v3
	v_min_u32_e32 v2, 0xff, v2
	v_cndmask_b32_e64 v2, v2, v226, s[4:5]
	v_lshl_add_u32 v2, v2, 2, s6
	ds_add_u32 v2, v223
	v_max_i32_e32 v2, 0xffffff80, v3
	s_waitcnt vmcnt(3)
	v_add_f32_e32 v3, v13, v13
	v_floor_f32_e32 v3, v3
	v_add_u32_e32 v2, 0x80, v2
	v_cvt_i32_f32_e32 v3, v3
	v_min_u32_e32 v2, 0xff, v2
	v_cndmask_b32_e64 v2, v2, v226, s[10:11]
	v_lshl_add_u32 v2, v2, 2, s6
	ds_add_u32 v2, v223
	v_max_i32_e32 v2, 0xffffff80, v3
	s_waitcnt vmcnt(2)
	v_add_f32_e32 v3, v14, v14
	v_floor_f32_e32 v3, v3
	v_add_u32_e32 v2, 0x80, v2
	v_cvt_i32_f32_e32 v3, v3
	v_min_u32_e32 v2, 0xff, v2
	v_cndmask_b32_e64 v2, v2, v226, s[12:13]
	v_lshl_add_u32 v2, v2, 2, s6
	ds_add_u32 v2, v223
	v_max_i32_e32 v2, 0xffffff80, v3
	s_waitcnt vmcnt(1)
	v_add_f32_e32 v3, v15, v15
	v_floor_f32_e32 v3, v3
	v_add_u32_e32 v2, 0x80, v2
	v_cvt_i32_f32_e32 v3, v3
	v_min_u32_e32 v2, 0xff, v2
	v_cndmask_b32_e64 v2, v2, v226, s[14:15]
	v_lshl_add_u32 v2, v2, 2, s6
	ds_add_u32 v2, v223
	v_max_i32_e32 v2, 0xffffff80, v3
	s_waitcnt vmcnt(0)
	v_add_f32_e32 v3, v16, v16
	v_floor_f32_e32 v3, v3
	v_add_u32_e32 v2, 0x80, v2
	v_cvt_i32_f32_e32 v3, v3
	v_min_u32_e32 v2, 0xff, v2
	v_cndmask_b32_e64 v2, v2, v226, s[16:17]
	v_lshl_add_u32 v2, v2, 2, s6
	ds_add_u32 v2, v223
	v_max_i32_e32 v2, 0xffffff80, v3
	v_add_u32_e32 v2, 0x80, v2
	v_min_u32_e32 v2, 0xff, v2
	v_cndmask_b32_e64 v2, v2, v226, s[18:19]
	v_lshl_add_u32 v2, v2, 2, s6
	ds_add_u32 v2, v223
	s_waitcnt lgkmcnt(0)
	ds_read_b128 v[2:5], v7
	v_readlane_b32 s8, v254, 12
	v_readlane_b32 s9, v254, 13
	s_waitcnt lgkmcnt(0)
	v_add_u32_e32 v18, v2, v3
	v_add3_u32 v19, v18, v4, v5
	v_mov_b32_e32 v18, v19
	s_nop 1
	v_add_u32_dpp v18, v18, v18 row_shr:1 row_mask:0xf bank_mask:0xf bound_ctrl:0
	s_nop 1
	v_add_u32_dpp v18, v18, v18 row_shr:2 row_mask:0xf bank_mask:0xf bound_ctrl:0
	s_nop 1
	v_add_u32_dpp v18, v18, v18 row_shr:4 row_mask:0xf bank_mask:0xf bound_ctrl:0
	s_nop 1
	v_add_u32_dpp v18, v18, v18 row_shr:8 row_mask:0xf bank_mask:0xf bound_ctrl:0
	s_nop 1
	v_add_u32_dpp v18, v18, v18 row_bcast:15 row_mask:0xa bank_mask:0xf
	s_nop 1
	v_add_u32_dpp v18, v18, v18 row_bcast:31 row_mask:0xc bank_mask:0xf
	s_nop 1
	v_readlane_b32 s8, v18, 63
	s_nop 1
	v_sub_u32_e32 v20, s8, v18
	v_add_u32_e32 v18, v20, v19
	v_mov_b32_e32 v19, v20
	v_add_u32_e32 v22, v19, v5
	v_cmp_gt_u32_e32 vcc, s63, v22
	v_mov_b32_e32 v20, 3
	v_mov_b32_e32 v21, v19
	s_and_saveexec_b64 s[8:9], vcc
	s_mov_b32 s88, 0xefa18f08
	s_cbranch_execz .LBB0_745
	v_add_u32_e32 v5, v22, v4
	v_cmp_gt_u32_e32 vcc, s63, v5
	v_mov_b32_e32 v20, 2
	s_and_saveexec_b64 s[48:49], vcc
	v_add_u32_e32 v4, v5, v3
	s_movk_i32 s50, 0xff
	v_cmp_lt_u32_e32 vcc, s50, v4
	s_nop 1
	v_cndmask_b32_e64 v20, 0, 1, vcc
	v_cndmask_b32_e32 v22, v4, v5, vcc
	v_cndmask_b32_e32 v4, v2, v3, vcc
	s_or_b64 exec, exec, s[48:49]
	v_mov_b32_e32 v5, v4
	v_mov_b32_e32 v21, v22

; #define WL1(J) if constexpr (J < NJ) { const unsigned long long w_ = __ballot(key[J] >= tau); const unsigned wl_ = (unsigned)w_, wh_ = (unsigned)(w_ >> 32); \
;                 asm volatile("s_nop 3\n\tv_writelane_b32 %0, %2, " #J "\n\tv_writelane_b32 %1, %3, " #J : "+v"(mlo), "+v"(mhi) : "s"(wl_), "s"(wh_)); }
; template <int NJ>
; __device__ __forceinline__ void select_rows(const GAS float* sr0, GAS unsigned long long* mb0, LAS unsigned* hist, LAS unsigned* kbuf, int ntl, int lane) {
;     ...
;             const bool have = (unsigned)lane < C;
;             const unsigned mykey = have ? hist[258 + lane] : 0u;
;             unsigned cgt = 0u;
;             for (unsigned i = 0; i < C; ++i) { const unsigned o = (unsigned)__builtin_amdgcn_readlane((int)mykey, (int)i); cgt += (o > mykey) ? 1u : 0u; }
;             unsigned t = (have && cgt < rem) ? mykey : 0xffffffffu;
; #pragma unroll
;             for (int o = 1; o < 64; o <<= 1) t = min(t, (unsigned)__shfl_xor((int)t, o));
;             tau = t;
;             const unsigned long long eqm = __ballot(have && mykey == tau);
;             cnteq = (unsigned)__popcll(eqm);
;             remf = rem - (unsigned)__builtin_amdgcn_readlane((int)cgt, eqm ? (int)__builtin_ctzll(eqm) : 0);
;             generic = cnteq > remf;
;         }
;         unsigned mlo = 0u, mhi = 0u;
;         if (!generic) {
;     ...
;             WL1(0) WL1(1) WL1(2) WL1(3) WL1(4) WL1(5) WL1(6) WL1(7) WL1(8) WL1(9) WL1(10) WL1(11) WL1(12) WL1(13) WL1(14) WL1(15)
;             WL1(16) WL1(17) WL1(18) WL1(19) WL1(20) WL1(21) WL1(22) WL1(23) WL1(24) WL1(25) WL1(26) WL1(27) WL1(28) WL1(29) WL1(30) WL1(31)
.LBB0_782:
	s_sub_i32 s48, 0x100, s52
	v_cmp_gt_u32_e64 s[8:9], s48, v3
	v_and_b32_e32 v17, 64, v224
	s_and_b64 s[8:9], vcc, s[8:9]
	v_add_u32_e32 v17, 64, v17
	v_xor_b32_e32 v18, 1, v224
	s_waitcnt lgkmcnt(0)
	v_cndmask_b32_e64 v5, -1, v2, s[8:9]
	s_nop 1
	v_min_u32_dpp v5, v5, v5 row_shr:1 row_mask:0xf bank_mask:0xf
	s_nop 1
	v_min_u32_dpp v5, v5, v5 row_shr:2 row_mask:0xf bank_mask:0xf
	s_nop 1
	v_min_u32_dpp v5, v5, v5 row_shr:4 row_mask:0xf bank_mask:0xf
	s_nop 1
	v_min_u32_dpp v5, v5, v5 row_shr:8 row_mask:0xf bank_mask:0xf
	s_nop 1
	v_min_u32_dpp v5, v5, v5 row_bcast:15 row_mask:0xa bank_mask:0xf
	s_nop 1
	v_min_u32_dpp v5, v5, v5 row_bcast:31 row_mask:0xc bank_mask:0xf
	s_nop 1
	v_readlane_b32 s8, v5, 63
	s_nop 1
	v_mov_b32_e32 v5, s8
	v_cmp_eq_u32_e64 s[8:9], v2, v5
	s_and_b64 s[8:9], vcc, s[8:9]
	s_nop 0
	v_cndmask_b32_e64 v2, 0, 1, s[8:9]
	v_cmp_ne_u32_e32 vcc, 0, v2
	s_bcnt1_i32_b64 s8, vcc
	s_ff1_i32_b64 s9, vcc
	s_cmp_lg_u64 vcc, 0
	s_cselect_b32 s9, s9, 0
	v_readlane_b32 s9, v3, s9
	s_sub_i32 s9, s48, s9
	s_cmp_ge_u32 s9, s8
	s_mov_b64 s[8:9], -1
	s_cbranch_scc0 .LBB0_784
	v_cmp_ge_u32_e32 vcc, v4, v5
	v_mov_b32_e32 v2, v0
	v_mov_b32_e32 v3, v0
	s_nop 3
	v_writelane_b32 v2, vcc_lo, 0
	v_writelane_b32 v3, vcc_hi, 0
	v_cmp_ge_u32_e32 vcc, v10, v5
	s_nop 3
	v_writelane_b32 v2, vcc_lo, 1
	v_writelane_b32 v3, vcc_hi, 1
	v_cmp_ge_u32_e32 vcc, v11, v5
	s_nop 3
	v_writelane_b32 v2, vcc_lo, 2
	v_writelane_b32 v3, vcc_hi, 2
	v_cmp_ge_u32_e32 vcc, v12, v5
	s_nop 3
	v_writelane_b32 v2, vcc_lo, 3
	v_writelane_b32 v3, vcc_hi, 3
	v_cmp_ge_u32_e32 vcc, v13, v5
	s_nop 3
	v_writelane_b32 v2, vcc_lo, 4
	v_writelane_b32 v3, vcc_hi, 4
	v_cmp_ge_u32_e32 vcc, v14, v5
	s_nop 3
	v_writelane_b32 v2, vcc_lo, 5
	v_writelane_b32 v3, vcc_hi, 5
	v_cmp_ge_u32_e32 vcc, v15, v5
	s_nop 3
	v_writelane_b32 v2, vcc_lo, 6
	v_writelane_b32 v3, vcc_hi, 6
	v_cmp_ge_u32_e32 vcc, v16, v5
	s_nop 3
	v_writelane_b32 v2, vcc_lo, 7
	v_writelane_b32 v3, vcc_hi, 7
	s_mov_b64 s[8:9], 0
